# epilogue row-scale loads hoisted: P4/P6/P7 epilogues preload 8 row scales at once instead of load+vmcnt0 per 16-row block
# speedup vs baseline: 1.0025x; 1.0025x over previous
.LBB0_638:
	s_mov_b32 s29, 0
	v_cvt_f32_i32_e32 v169, v125
	v_mbcnt_lo_u32_b32 v144, -1, s29
	v_mbcnt_hi_u32_b32 v166, -1, v144
	s_lshl_b32 s29, s70, 8
	v_ashrrev_i32_e32 v144, 1, v166
	s_or_b32 s29, s29, s59
	v_and_b32_e32 v144, -8, v144
	v_add_u32_e32 v144, s29, v144
	v_ashrrev_i32_e32 v145, 31, v144
	v_lshl_add_u64 v[146:147], v[144:145], 2, s[10:11]
	global_load_dwordx4 v[148:151], v[146:147], off
	global_load_dwordx4 v[152:155], v[146:147], off offset:16
	global_load_dwordx4 v[156:159], v[146:147], off offset:528
	global_load_dwordx4 v[160:163], v[146:147], off offset:512
	v_and_or_b32 v146, v166, 15, s27
	v_ashrrev_i32_e32 v147, 31, v146
	v_lshl_add_u64 v[166:167], v[146:147], 3, s[8:9]
	global_load_dword v224, v[166:167], off offset:132
	global_load_dword v226, v[166:167], off offset:260
	global_load_dword v228, v[166:167], off offset:388
	global_load_dword v230, v[166:167], off offset:1028
	global_load_dword v232, v[166:167], off offset:1156
	global_load_dword v234, v[166:167], off offset:1284
	global_load_dword v236, v[166:167], off offset:1412
	global_load_dword v166, v[166:167], off offset:4
	v_cvt_f32_i32_e32 v168, v124
	v_cvt_f32_i32_e32 v171, v127
	v_cvt_f32_i32_e32 v170, v126
	v_cvt_f32_i32_e32 v173, v121
	v_cvt_f32_i32_e32 v172, v120
	v_cvt_f32_i32_e32 v181, v113
	v_cvt_f32_i32_e32 v180, v112
	v_lshlrev_b64 v[112:113], 13, v[146:147]
	v_cvt_f32_i32_e32 v175, v123
	v_cvt_f32_i32_e32 v174, v122
	v_cvt_f32_i32_e32 v183, v115
	v_cvt_f32_i32_e32 v182, v114
	v_lshl_add_u64 v[114:115], s[16:17], 0, v[112:113]
	v_lshlrev_b64 v[112:113], 1, v[144:145]
	v_cvt_f32_i32_e32 v177, v117
	v_cvt_f32_i32_e32 v176, v116
	v_cvt_f32_i32_e32 v179, v119
	v_cvt_f32_i32_e32 v178, v118
	v_lshl_add_u64 v[188:189], v[114:115], 0, v[112:113]
	v_or_b32_e32 v184, 16, v146
	v_ashrrev_i32_e32 v185, 31, v184
	v_lshl_add_u64 v[186:187], v[184:185], 3, s[8:9]
	v_cvt_f32_i32_e32 v109, v109
	v_cvt_f32_i32_e32 v108, v108
	v_cvt_f32_i32_e32 v111, v111
	v_cvt_f32_i32_e32 v110, v110
	v_cvt_f32_i32_e32 v105, v105
	v_cvt_f32_i32_e32 v104, v104
	v_cvt_f32_i32_e32 v107, v107
	v_cvt_f32_i32_e32 v106, v106
	v_cvt_f32_i32_e32 v97, v97
	v_cvt_f32_i32_e32 v96, v96
	v_cvt_f32_i32_e32 v99, v99
	v_cvt_f32_i32_e32 v98, v98
	v_cvt_f32_i32_e32 v101, v101
	v_cvt_f32_i32_e32 v100, v100
	v_cvt_f32_i32_e32 v103, v103
	v_cvt_f32_i32_e32 v102, v102
	v_cvt_f32_i32_e32 v93, v93
	v_cvt_f32_i32_e32 v92, v92
	v_cvt_f32_i32_e32 v95, v95
	v_cvt_f32_i32_e32 v94, v94
	v_cvt_f32_i32_e32 v89, v89
	v_cvt_f32_i32_e32 v88, v88
	v_cvt_f32_i32_e32 v91, v91
	v_cvt_f32_i32_e32 v90, v90
	v_cvt_f32_i32_e32 v81, v81
	v_cvt_f32_i32_e32 v80, v80
	v_cvt_f32_i32_e32 v83, v83
	v_cvt_f32_i32_e32 v82, v82
	v_cvt_f32_i32_e32 v85, v85
	v_cvt_f32_i32_e32 v84, v84
	v_cvt_f32_i32_e32 v87, v87
	v_cvt_f32_i32_e32 v86, v86
	v_cvt_f32_i32_e32 v77, v77
	v_cvt_f32_i32_e32 v76, v76
	v_cvt_f32_i32_e32 v79, v79
	v_cvt_f32_i32_e32 v78, v78
	v_cvt_f32_i32_e32 v73, v73
	v_cvt_f32_i32_e32 v72, v72
	v_cvt_f32_i32_e32 v75, v75
	v_cvt_f32_i32_e32 v74, v74
	v_cvt_f32_i32_e32 v65, v65
	v_cvt_f32_i32_e32 v64, v64
	v_cvt_f32_i32_e32 v67, v67
	v_cvt_f32_i32_e32 v66, v66
	v_cvt_f32_i32_e32 v69, v69
	v_cvt_f32_i32_e32 v68, v68
	v_cvt_f32_i32_e32 v71, v71
	v_cvt_f32_i32_e32 v70, v70
	v_cvt_f32_i32_e32 v61, v61
	v_cvt_f32_i32_e32 v60, v60
	s_waitcnt vmcnt(0)
	v_pk_mul_f32 v[114:115], v[150:151], s[24:25] op_sel_hi:[1,0]
	v_pk_mul_f32 v[116:117], v[148:149], s[24:25] op_sel_hi:[1,0]
	v_pk_mul_f32 v[120:121], v[152:153], s[24:25] op_sel_hi:[1,0]
	v_pk_mul_f32 v[118:119], v[154:155], s[24:25] op_sel_hi:[1,0]
	v_pk_mul_f32 v[122:123], v[162:163], s[24:25] op_sel_hi:[1,0]
	v_pk_mul_f32 v[124:125], v[160:161], s[24:25] op_sel_hi:[1,0]
	v_pk_mul_f32 v[126:127], v[158:159], s[24:25] op_sel_hi:[1,0]
	v_pk_mul_f32 v[144:145], v[156:157], s[24:25] op_sel_hi:[1,0]
	v_pk_mul_f32 v[148:149], v[114:115], v[166:167] op_sel_hi:[1,0]
	v_pk_mul_f32 v[150:151], v[116:117], v[166:167] op_sel_hi:[1,0]
	v_pk_mul_f32 v[154:155], v[120:121], v[166:167] op_sel_hi:[1,0]
	v_pk_mul_f32 v[152:153], v[118:119], v[166:167] op_sel_hi:[1,0]
	v_pk_mul_f32 v[156:157], v[122:123], v[166:167] op_sel_hi:[1,0]
	v_pk_mul_f32 v[158:159], v[124:125], v[166:167] op_sel_hi:[1,0]
	v_pk_mul_f32 v[160:161], v[126:127], v[166:167] op_sel_hi:[1,0]
	v_pk_mul_f32 v[162:163], v[144:145], v[166:167] op_sel_hi:[1,0]
	v_pk_mul_f32 v[166:167], v[148:149], v[170:171]
	v_pk_mul_f32 v[148:149], v[150:151], v[168:169]
	v_pk_mul_f32 v[150:151], v[154:155], v[172:173]
	v_pk_mul_f32 v[152:153], v[152:153], v[174:175]
	v_cvt_pk_bf16_f32 v148, v148, v149
	v_cvt_pk_bf16_f32 v149, v166, v167
	v_cvt_pk_bf16_f32 v150, v150, v151
	v_pk_mul_f32 v[154:155], v[156:157], v[178:179]
	v_cvt_pk_bf16_f32 v151, v152, v153
	v_pk_mul_f32 v[156:157], v[158:159], v[176:177]
	v_pk_mul_f32 v[158:159], v[160:161], v[182:183]
	v_pk_mul_f32 v[160:161], v[162:163], v[180:181]
	global_store_dwordx4 v[188:189], v[148:151], off
	v_lshlrev_b64 v[152:153], 13, v[184:185]
	v_lshl_add_u64 v[152:153], s[16:17], 0, v[152:153]
	v_cvt_pk_bf16_f32 v148, v156, v157
	v_cvt_pk_bf16_f32 v149, v154, v155
	v_cvt_pk_bf16_f32 v150, v160, v161
	v_cvt_pk_bf16_f32 v151, v158, v159
	global_store_dwordx4 v[188:189], v[148:151], off offset:256
	s_nop 0
	v_lshl_add_u64 v[152:153], v[152:153], 0, v[112:113]
	v_or_b32_e32 v150, 32, v146
	v_ashrrev_i32_e32 v151, 31, v150
	v_lshl_add_u64 v[154:155], v[150:151], 3, s[8:9]
	v_cvt_f32_i32_e32 v63, v63
	v_cvt_f32_i32_e32 v62, v62
	v_cvt_f32_i32_e32 v57, v57
	v_cvt_f32_i32_e32 v56, v56
	v_cvt_f32_i32_e32 v59, v59
	v_cvt_f32_i32_e32 v58, v58
	v_cvt_f32_i32_e32 v49, v49
	v_cvt_f32_i32_e32 v48, v48
	v_cvt_f32_i32_e32 v51, v51
	v_cvt_f32_i32_e32 v50, v50
	v_cvt_f32_i32_e32 v53, v53
	v_cvt_f32_i32_e32 v52, v52
	v_cvt_f32_i32_e32 v55, v55
	v_cvt_f32_i32_e32 v54, v54
	v_cvt_f32_i32_e32 v45, v45
	v_cvt_f32_i32_e32 v44, v44
	v_cvt_f32_i32_e32 v47, v47
	v_cvt_f32_i32_e32 v46, v46
	v_cvt_f32_i32_e32 v41, v41
	v_cvt_f32_i32_e32 v40, v40
	v_cvt_f32_i32_e32 v43, v43
	v_cvt_f32_i32_e32 v42, v42
	v_cvt_f32_i32_e32 v33, v33
	v_cvt_f32_i32_e32 v32, v32
	v_cvt_f32_i32_e32 v35, v35
	v_cvt_f32_i32_e32 v34, v34
	v_cvt_f32_i32_e32 v37, v37
	v_cvt_f32_i32_e32 v36, v36
	v_cvt_f32_i32_e32 v39, v39
	v_cvt_f32_i32_e32 v38, v38
	v_cvt_f32_i32_e32 v29, v29
	v_cvt_f32_i32_e32 v28, v28
	v_cvt_f32_i32_e32 v31, v31
	v_cvt_f32_i32_e32 v30, v30
	v_cvt_f32_i32_e32 v25, v25
	v_cvt_f32_i32_e32 v24, v24
	v_cvt_f32_i32_e32 v27, v27
	v_cvt_f32_i32_e32 v26, v26
	v_cvt_f32_i32_e32 v17, v17
	v_cvt_f32_i32_e32 v16, v16
	v_cvt_f32_i32_e32 v19, v19
	v_cvt_f32_i32_e32 v18, v18
	v_cvt_f32_i32_e32 v21, v21
	v_cvt_f32_i32_e32 v20, v20
	v_cvt_f32_i32_e32 v23, v23
	v_cvt_f32_i32_e32 v22, v22
	v_cvt_f32_i32_e32 v13, v13
	v_cvt_f32_i32_e32 v12, v12
	v_cvt_f32_i32_e32 v15, v15
	v_cvt_f32_i32_e32 v14, v14
	v_cvt_f32_i32_e32 v9, v9
	v_cvt_f32_i32_e32 v8, v8
	v_cvt_f32_i32_e32 v11, v11
	v_cvt_f32_i32_e32 v10, v10
	v_cvt_f32_i32_e32 v1, v1
	v_cvt_f32_i32_e32 v0, v0
	v_cvt_f32_i32_e32 v3, v3
	v_cvt_f32_i32_e32 v2, v2
	v_cvt_f32_i32_e32 v5, v5
	v_cvt_f32_i32_e32 v4, v4
	v_cvt_f32_i32_e32 v7, v7
	v_cvt_f32_i32_e32 v6, v6
	s_andn2_b64 vcc, exec, s[4:5]
	s_mov_b64 s[4:5], -1
	s_nop 0
	v_pk_mul_f32 v[156:157], v[114:115], v[224:225] op_sel_hi:[1,0]
	v_pk_mul_f32 v[158:159], v[116:117], v[224:225] op_sel_hi:[1,0]
	v_pk_mul_f32 v[160:161], v[118:119], v[224:225] op_sel_hi:[1,0]
	v_pk_mul_f32 v[162:163], v[120:121], v[224:225] op_sel_hi:[1,0]
	v_pk_mul_f32 v[166:167], v[122:123], v[224:225] op_sel_hi:[1,0]
	v_pk_mul_f32 v[168:169], v[124:125], v[224:225] op_sel_hi:[1,0]
	v_pk_mul_f32 v[170:171], v[126:127], v[224:225] op_sel_hi:[1,0]
	v_pk_mul_f32 v[148:149], v[144:145], v[224:225] op_sel_hi:[1,0]
	v_pk_mul_f32 v[110:111], v[156:157], v[110:111]
	v_pk_mul_f32 v[108:109], v[158:159], v[108:109]
	v_pk_mul_f32 v[106:107], v[160:161], v[106:107]
	v_pk_mul_f32 v[104:105], v[162:163], v[104:105]
	v_pk_mul_f32 v[156:157], v[170:171], v[98:99]
	v_pk_mul_f32 v[148:149], v[148:149], v[96:97]
	v_cvt_pk_bf16_f32 v96, v108, v109
	v_cvt_pk_bf16_f32 v97, v110, v111
	v_cvt_pk_bf16_f32 v98, v104, v105
	v_cvt_pk_bf16_f32 v99, v106, v107
	v_pk_mul_f32 v[102:103], v[166:167], v[102:103]
	v_pk_mul_f32 v[100:101], v[168:169], v[100:101]
	global_store_dwordx4 v[152:153], v[96:99], off
	s_nop 1
	v_cvt_pk_bf16_f32 v96, v100, v101
	v_cvt_pk_bf16_f32 v97, v102, v103
	v_cvt_pk_bf16_f32 v98, v148, v149
	v_cvt_pk_bf16_f32 v99, v156, v157
	global_store_dwordx4 v[152:153], v[96:99], off offset:256
	s_nop 0
	v_lshlrev_b64 v[100:101], 13, v[150:151]
	v_or_b32_e32 v98, 48, v146
	v_lshl_add_u64 v[100:101], s[16:17], 0, v[100:101]
	v_ashrrev_i32_e32 v99, 31, v98
	v_lshl_add_u64 v[100:101], v[100:101], 0, v[112:113]
	v_lshl_add_u64 v[102:103], v[98:99], 3, s[8:9]
	s_nop 0
	v_pk_mul_f32 v[104:105], v[114:115], v[226:227] op_sel_hi:[1,0]
	v_pk_mul_f32 v[106:107], v[116:117], v[226:227] op_sel_hi:[1,0]
	v_pk_mul_f32 v[108:109], v[118:119], v[226:227] op_sel_hi:[1,0]
	v_pk_mul_f32 v[110:111], v[120:121], v[226:227] op_sel_hi:[1,0]
	v_pk_mul_f32 v[148:149], v[122:123], v[226:227] op_sel_hi:[1,0]
	v_pk_mul_f32 v[150:151], v[124:125], v[226:227] op_sel_hi:[1,0]
	v_pk_mul_f32 v[152:153], v[126:127], v[226:227] op_sel_hi:[1,0]
	v_pk_mul_f32 v[96:97], v[144:145], v[226:227] op_sel_hi:[1,0]
	v_pk_mul_f32 v[94:95], v[104:105], v[94:95]
	v_pk_mul_f32 v[92:93], v[106:107], v[92:93]
	v_pk_mul_f32 v[90:91], v[108:109], v[90:91]
	v_pk_mul_f32 v[88:89], v[110:111], v[88:89]
	v_pk_mul_f32 v[104:105], v[152:153], v[82:83]
	v_pk_mul_f32 v[96:97], v[96:97], v[80:81]
	v_cvt_pk_bf16_f32 v80, v92, v93
	v_cvt_pk_bf16_f32 v81, v94, v95
	v_cvt_pk_bf16_f32 v82, v88, v89
	v_cvt_pk_bf16_f32 v83, v90, v91
	v_pk_mul_f32 v[86:87], v[148:149], v[86:87]
	v_pk_mul_f32 v[84:85], v[150:151], v[84:85]
	global_store_dwordx4 v[100:101], v[80:83], off
	s_nop 1
	v_cvt_pk_bf16_f32 v80, v84, v85
	v_cvt_pk_bf16_f32 v81, v86, v87
	v_cvt_pk_bf16_f32 v82, v96, v97
	v_cvt_pk_bf16_f32 v83, v104, v105
	global_store_dwordx4 v[100:101], v[80:83], off offset:256
	s_nop 0
	v_lshlrev_b64 v[84:85], 13, v[98:99]
	v_add_u32_e32 v82, 0x80, v146
	v_lshl_add_u64 v[84:85], s[16:17], 0, v[84:85]
	v_ashrrev_i32_e32 v83, 31, v82
	v_lshl_add_u64 v[84:85], v[84:85], 0, v[112:113]
	v_lshl_add_u64 v[86:87], v[82:83], 3, s[8:9]
	s_nop 0
	v_pk_mul_f32 v[88:89], v[114:115], v[228:229] op_sel_hi:[1,0]
	v_pk_mul_f32 v[90:91], v[116:117], v[228:229] op_sel_hi:[1,0]
	v_pk_mul_f32 v[92:93], v[118:119], v[228:229] op_sel_hi:[1,0]
	v_pk_mul_f32 v[94:95], v[120:121], v[228:229] op_sel_hi:[1,0]
	v_pk_mul_f32 v[96:97], v[122:123], v[228:229] op_sel_hi:[1,0]
	v_pk_mul_f32 v[98:99], v[124:125], v[228:229] op_sel_hi:[1,0]
	v_pk_mul_f32 v[100:101], v[126:127], v[228:229] op_sel_hi:[1,0]
	v_pk_mul_f32 v[80:81], v[144:145], v[228:229] op_sel_hi:[1,0]
	v_pk_mul_f32 v[78:79], v[88:89], v[78:79]
	v_pk_mul_f32 v[76:77], v[90:91], v[76:77]
	v_pk_mul_f32 v[74:75], v[92:93], v[74:75]
	v_pk_mul_f32 v[72:73], v[94:95], v[72:73]
	v_pk_mul_f32 v[88:89], v[100:101], v[66:67]
	v_pk_mul_f32 v[80:81], v[80:81], v[64:65]
	v_cvt_pk_bf16_f32 v64, v76, v77
	v_cvt_pk_bf16_f32 v65, v78, v79
	v_cvt_pk_bf16_f32 v66, v72, v73
	v_cvt_pk_bf16_f32 v67, v74, v75
	v_pk_mul_f32 v[70:71], v[96:97], v[70:71]
	v_pk_mul_f32 v[68:69], v[98:99], v[68:69]
	global_store_dwordx4 v[84:85], v[64:67], off
	s_nop 1
	v_cvt_pk_bf16_f32 v64, v68, v69
	v_cvt_pk_bf16_f32 v65, v70, v71
	v_cvt_pk_bf16_f32 v66, v80, v81
	v_cvt_pk_bf16_f32 v67, v88, v89
	global_store_dwordx4 v[84:85], v[64:67], off offset:256
	s_nop 0
	v_lshlrev_b64 v[68:69], 13, v[82:83]
	v_add_u32_e32 v66, 0x90, v146
	v_lshl_add_u64 v[68:69], s[16:17], 0, v[68:69]
	v_ashrrev_i32_e32 v67, 31, v66
	v_lshl_add_u64 v[68:69], v[68:69], 0, v[112:113]
	v_lshl_add_u64 v[70:71], v[66:67], 3, s[8:9]
	s_nop 0
	v_pk_mul_f32 v[72:73], v[114:115], v[230:231] op_sel_hi:[1,0]
	v_pk_mul_f32 v[74:75], v[116:117], v[230:231] op_sel_hi:[1,0]
	v_pk_mul_f32 v[76:77], v[118:119], v[230:231] op_sel_hi:[1,0]
	v_pk_mul_f32 v[78:79], v[120:121], v[230:231] op_sel_hi:[1,0]
	v_pk_mul_f32 v[80:81], v[122:123], v[230:231] op_sel_hi:[1,0]
	v_pk_mul_f32 v[82:83], v[124:125], v[230:231] op_sel_hi:[1,0]
	v_pk_mul_f32 v[84:85], v[126:127], v[230:231] op_sel_hi:[1,0]
	v_pk_mul_f32 v[64:65], v[144:145], v[230:231] op_sel_hi:[1,0]
	v_pk_mul_f32 v[62:63], v[72:73], v[62:63]
	v_pk_mul_f32 v[60:61], v[74:75], v[60:61]
	v_pk_mul_f32 v[58:59], v[76:77], v[58:59]
	v_pk_mul_f32 v[56:57], v[78:79], v[56:57]
	v_pk_mul_f32 v[72:73], v[84:85], v[50:51]
	v_pk_mul_f32 v[64:65], v[64:65], v[48:49]
	v_cvt_pk_bf16_f32 v48, v60, v61
	v_cvt_pk_bf16_f32 v49, v62, v63
	v_cvt_pk_bf16_f32 v50, v56, v57
	v_cvt_pk_bf16_f32 v51, v58, v59
	v_pk_mul_f32 v[54:55], v[80:81], v[54:55]
	v_pk_mul_f32 v[52:53], v[82:83], v[52:53]
	global_store_dwordx4 v[68:69], v[48:51], off
	s_nop 1
	v_cvt_pk_bf16_f32 v48, v52, v53
	v_cvt_pk_bf16_f32 v49, v54, v55
	v_cvt_pk_bf16_f32 v50, v64, v65
	v_cvt_pk_bf16_f32 v51, v72, v73
	global_store_dwordx4 v[68:69], v[48:51], off offset:256
	s_nop 0
	v_lshlrev_b64 v[52:53], 13, v[66:67]
	v_add_u32_e32 v50, 0xa0, v146
	v_lshl_add_u64 v[52:53], s[16:17], 0, v[52:53]
	v_ashrrev_i32_e32 v51, 31, v50
	v_lshl_add_u64 v[52:53], v[52:53], 0, v[112:113]
	v_lshl_add_u64 v[54:55], v[50:51], 3, s[8:9]
	s_nop 0
	v_pk_mul_f32 v[56:57], v[114:115], v[232:233] op_sel_hi:[1,0]
	v_pk_mul_f32 v[58:59], v[116:117], v[232:233] op_sel_hi:[1,0]
	v_pk_mul_f32 v[60:61], v[118:119], v[232:233] op_sel_hi:[1,0]
	v_pk_mul_f32 v[62:63], v[120:121], v[232:233] op_sel_hi:[1,0]
	v_pk_mul_f32 v[64:65], v[122:123], v[232:233] op_sel_hi:[1,0]
	v_pk_mul_f32 v[66:67], v[124:125], v[232:233] op_sel_hi:[1,0]
	v_pk_mul_f32 v[68:69], v[126:127], v[232:233] op_sel_hi:[1,0]
	v_pk_mul_f32 v[48:49], v[144:145], v[232:233] op_sel_hi:[1,0]
	v_pk_mul_f32 v[46:47], v[56:57], v[46:47]
	v_pk_mul_f32 v[44:45], v[58:59], v[44:45]
	v_pk_mul_f32 v[42:43], v[60:61], v[42:43]
	v_pk_mul_f32 v[40:41], v[62:63], v[40:41]
	v_pk_mul_f32 v[56:57], v[68:69], v[34:35]
	v_pk_mul_f32 v[48:49], v[48:49], v[32:33]
	v_cvt_pk_bf16_f32 v32, v44, v45
	v_cvt_pk_bf16_f32 v33, v46, v47
	v_cvt_pk_bf16_f32 v34, v40, v41
	v_cvt_pk_bf16_f32 v35, v42, v43
	v_pk_mul_f32 v[38:39], v[64:65], v[38:39]
	v_pk_mul_f32 v[36:37], v[66:67], v[36:37]
	global_store_dwordx4 v[52:53], v[32:35], off
	s_nop 1
	v_cvt_pk_bf16_f32 v32, v36, v37
	v_cvt_pk_bf16_f32 v33, v38, v39
	v_cvt_pk_bf16_f32 v34, v48, v49
	v_cvt_pk_bf16_f32 v35, v56, v57
	global_store_dwordx4 v[52:53], v[32:35], off offset:256
	s_nop 0
	v_lshlrev_b64 v[36:37], 13, v[50:51]
	v_add_u32_e32 v34, 0xb0, v146
	v_lshl_add_u64 v[36:37], s[16:17], 0, v[36:37]
	v_ashrrev_i32_e32 v35, 31, v34
	v_lshl_add_u64 v[36:37], v[36:37], 0, v[112:113]
	v_lshl_add_u64 v[38:39], v[34:35], 3, s[8:9]
	s_nop 0
	v_pk_mul_f32 v[40:41], v[114:115], v[234:235] op_sel_hi:[1,0]
	v_pk_mul_f32 v[42:43], v[116:117], v[234:235] op_sel_hi:[1,0]
	v_pk_mul_f32 v[44:45], v[118:119], v[234:235] op_sel_hi:[1,0]
	v_pk_mul_f32 v[46:47], v[120:121], v[234:235] op_sel_hi:[1,0]
	v_pk_mul_f32 v[48:49], v[122:123], v[234:235] op_sel_hi:[1,0]
	v_pk_mul_f32 v[50:51], v[124:125], v[234:235] op_sel_hi:[1,0]
	v_pk_mul_f32 v[52:53], v[126:127], v[234:235] op_sel_hi:[1,0]
	v_pk_mul_f32 v[32:33], v[144:145], v[234:235] op_sel_hi:[1,0]
	v_pk_mul_f32 v[30:31], v[40:41], v[30:31]
	v_pk_mul_f32 v[28:29], v[42:43], v[28:29]
	v_pk_mul_f32 v[26:27], v[44:45], v[26:27]
	v_pk_mul_f32 v[24:25], v[46:47], v[24:25]
	v_pk_mul_f32 v[40:41], v[52:53], v[18:19]
	v_pk_mul_f32 v[32:33], v[32:33], v[16:17]
	v_cvt_pk_bf16_f32 v16, v28, v29
	v_cvt_pk_bf16_f32 v17, v30, v31
	v_cvt_pk_bf16_f32 v18, v24, v25
	v_cvt_pk_bf16_f32 v19, v26, v27
	v_pk_mul_f32 v[22:23], v[48:49], v[22:23]
	v_pk_mul_f32 v[20:21], v[50:51], v[20:21]
	global_store_dwordx4 v[36:37], v[16:19], off
	s_nop 1
	v_cvt_pk_bf16_f32 v16, v20, v21
	v_cvt_pk_bf16_f32 v17, v22, v23
	v_cvt_pk_bf16_f32 v18, v32, v33
	v_cvt_pk_bf16_f32 v19, v40, v41
	global_store_dwordx4 v[36:37], v[16:19], off offset:256
	s_nop 0
	s_nop 0
	v_pk_mul_f32 v[20:21], v[114:115], v[236:237] op_sel_hi:[1,0]
	v_lshlrev_b64 v[18:19], 13, v[34:35]
	v_lshl_add_u64 v[18:19], s[16:17], 0, v[18:19]
	v_pk_mul_f32 v[22:23], v[116:117], v[236:237] op_sel_hi:[1,0]
	v_pk_mul_f32 v[24:25], v[118:119], v[236:237] op_sel_hi:[1,0]
	v_pk_mul_f32 v[26:27], v[120:121], v[236:237] op_sel_hi:[1,0]
	v_pk_mul_f32 v[28:29], v[122:123], v[236:237] op_sel_hi:[1,0]
	v_pk_mul_f32 v[30:31], v[124:125], v[236:237] op_sel_hi:[1,0]
	v_pk_mul_f32 v[32:33], v[126:127], v[236:237] op_sel_hi:[1,0]
	v_pk_mul_f32 v[16:17], v[144:145], v[236:237] op_sel_hi:[1,0]
	v_lshl_add_u64 v[18:19], v[18:19], 0, v[112:113]
	v_pk_mul_f32 v[14:15], v[20:21], v[14:15]
	v_pk_mul_f32 v[12:13], v[22:23], v[12:13]
	v_pk_mul_f32 v[10:11], v[24:25], v[10:11]
	v_pk_mul_f32 v[8:9], v[26:27], v[8:9]
	v_pk_mul_f32 v[20:21], v[32:33], v[2:3]
	v_pk_mul_f32 v[16:17], v[16:17], v[0:1]
	v_cvt_pk_bf16_f32 v0, v12, v13
	v_cvt_pk_bf16_f32 v1, v14, v15
	v_cvt_pk_bf16_f32 v2, v8, v9
	v_cvt_pk_bf16_f32 v3, v10, v11
	v_pk_mul_f32 v[6:7], v[28:29], v[6:7]
	v_pk_mul_f32 v[4:5], v[30:31], v[4:5]
	global_store_dwordx4 v[18:19], v[0:3], off
	s_nop 1
	v_cvt_pk_bf16_f32 v0, v4, v5
	v_cvt_pk_bf16_f32 v1, v6, v7
	v_cvt_pk_bf16_f32 v2, v16, v17
	v_cvt_pk_bf16_f32 v3, v20, v21
	global_store_dwordx4 v[18:19], v[0:3], off offset:256
	s_cbranch_vccnz .LBB0_629
	s_andn2_b64 vcc, exec, s[6:7]
	s_cbranch_vccnz .LBB0_628
	s_barrier
	s_branch .LBB0_628

.LBB0_774:
	s_mov_b32 s39, 0
	v_cvt_f32_i32_e32 v175, v127
	v_mbcnt_lo_u32_b32 v144, -1, s39
	v_mbcnt_hi_u32_b32 v146, -1, v144
	v_ashrrev_i32_e32 v144, 1, v146
	s_lshl_b32 s39, s67, 8
	v_and_b32_e32 v148, -8, v144
	s_or_b32 s39, s39, s62
	v_add_u32_e32 v144, s39, v148
	v_ashrrev_i32_e32 v145, 31, v144
	s_lshl_b32 s39, s52, 8
	v_lshl_add_u64 v[144:145], v[144:145], 2, s[24:25]
	s_add_i32 s39, s39, s61
	global_load_dwordx4 v[156:159], v[144:145], off offset:16
	global_load_dwordx4 v[160:163], v[144:145], off
	global_load_dwordx4 v[164:167], v[144:145], off offset:528
	global_load_dwordx4 v[168:171], v[144:145], off offset:512
	v_and_or_b32 v144, v146, 15, s39
	v_ashrrev_i32_e32 v145, 31, v144
	v_lshl_add_u64 v[150:151], v[144:145], 2, s[22:23]
	global_load_dword v224, v[150:151], off offset:64
	global_load_dword v226, v[150:151], off offset:128
	global_load_dword v228, v[150:151], off offset:192
	global_load_dword v230, v[150:151], off offset:512
	global_load_dword v232, v[150:151], off offset:576
	global_load_dword v234, v[150:151], off offset:640
	global_load_dword v236, v[150:151], off offset:704
	global_load_dword v172, v[150:151], off
	s_lshl_b32 s39, s67, 7
	s_or_b32 s39, s39, s62
	v_cvt_f32_i32_e32 v174, v126
	v_cvt_f32_i32_e32 v177, v125
	v_cvt_f32_i32_e32 v176, v124
	v_cvt_f32_i32_e32 v188, v114
	v_add_u32_e32 v114, s39, v148
	v_mov_b64_e32 v[146:147], s[18:19]
	v_cvt_f32_i32_e32 v179, v123
	v_cvt_f32_i32_e32 v178, v122
	v_cvt_f32_i32_e32 v181, v121
	v_cvt_f32_i32_e32 v180, v120
	v_cvt_f32_i32_e32 v183, v117
	v_cvt_f32_i32_e32 v182, v116
	v_cvt_f32_i32_e32 v185, v119
	v_cvt_f32_i32_e32 v184, v118
	v_cvt_f32_i32_e32 v187, v113
	v_cvt_f32_i32_e32 v186, v112
	v_cvt_f32_i32_e32 v189, v115
	v_ashrrev_i32_e32 v115, 31, v114
	v_mad_i64_i32 v[112:113], s[54:55], v144, s74, v[146:147]
	v_lshlrev_b64 v[116:117], 1, v[114:115]
	v_lshl_add_u64 v[190:191], v[112:113], 0, v[116:117]
	v_cvt_f32_i32_e32 v111, v111
	v_cvt_f32_i32_e32 v110, v110
	v_cvt_f32_i32_e32 v109, v109
	v_cvt_f32_i32_e32 v108, v108
	v_cvt_f32_i32_e32 v107, v107
	v_cvt_f32_i32_e32 v106, v106
	v_cvt_f32_i32_e32 v105, v105
	v_cvt_f32_i32_e32 v104, v104
	v_cvt_f32_i32_e32 v101, v101
	v_cvt_f32_i32_e32 v100, v100
	v_cvt_f32_i32_e32 v103, v103
	v_cvt_f32_i32_e32 v102, v102
	v_cvt_f32_i32_e32 v97, v97
	v_cvt_f32_i32_e32 v96, v96
	v_cvt_f32_i32_e32 v99, v99
	v_cvt_f32_i32_e32 v98, v98
	v_cvt_f32_i32_e32 v95, v95
	v_cvt_f32_i32_e32 v94, v94
	v_cvt_f32_i32_e32 v93, v93
	v_cvt_f32_i32_e32 v92, v92
	v_cvt_f32_i32_e32 v91, v91
	v_cvt_f32_i32_e32 v90, v90
	v_cvt_f32_i32_e32 v89, v89
	v_cvt_f32_i32_e32 v88, v88
	v_cvt_f32_i32_e32 v85, v85
	v_cvt_f32_i32_e32 v84, v84
	v_cvt_f32_i32_e32 v87, v87
	v_cvt_f32_i32_e32 v86, v86
	v_cvt_f32_i32_e32 v81, v81
	v_cvt_f32_i32_e32 v80, v80
	v_cvt_f32_i32_e32 v83, v83
	v_cvt_f32_i32_e32 v82, v82
	v_cvt_f32_i32_e32 v79, v79
	v_cvt_f32_i32_e32 v78, v78
	v_cvt_f32_i32_e32 v77, v77
	v_cvt_f32_i32_e32 v76, v76
	v_cvt_f32_i32_e32 v75, v75
	v_cvt_f32_i32_e32 v74, v74
	v_cvt_f32_i32_e32 v73, v73
	v_cvt_f32_i32_e32 v72, v72
	v_cvt_f32_i32_e32 v69, v69
	v_cvt_f32_i32_e32 v68, v68
	v_cvt_f32_i32_e32 v71, v71
	v_cvt_f32_i32_e32 v70, v70
	v_cvt_f32_i32_e32 v65, v65
	v_cvt_f32_i32_e32 v64, v64
	v_cvt_f32_i32_e32 v67, v67
	v_cvt_f32_i32_e32 v66, v66
	v_cvt_f32_i32_e32 v63, v63
	s_waitcnt vmcnt(0)
	v_pk_mul_f32 v[122:123], v[158:159], s[30:31] op_sel_hi:[1,0]
	v_pk_mul_f32 v[118:119], v[162:163], s[30:31] op_sel_hi:[1,0]
	v_pk_mul_f32 v[120:121], v[160:161], s[30:31] op_sel_hi:[1,0]
	v_pk_mul_f32 v[124:125], v[156:157], s[30:31] op_sel_hi:[1,0]
	v_pk_mul_f32 v[112:113], v[170:171], s[30:31] op_sel_hi:[1,0]
	v_pk_mul_f32 v[126:127], v[168:169], s[30:31] op_sel_hi:[1,0]
	v_pk_mul_f32 v[114:115], v[166:167], s[30:31] op_sel_hi:[1,0]
	v_pk_mul_f32 v[148:149], v[164:165], s[30:31] op_sel_hi:[1,0]
	v_pk_mul_f32 v[156:157], v[118:119], v[172:173] op_sel_hi:[1,0]
	v_pk_mul_f32 v[158:159], v[120:121], v[172:173] op_sel_hi:[1,0]
	v_pk_mul_f32 v[160:161], v[122:123], v[172:173] op_sel_hi:[1,0]
	v_pk_mul_f32 v[162:163], v[124:125], v[172:173] op_sel_hi:[1,0]
	v_pk_mul_f32 v[164:165], v[126:127], v[172:173] op_sel_hi:[1,0]
	v_pk_mul_f32 v[166:167], v[112:113], v[172:173] op_sel_hi:[1,0]
	v_pk_mul_f32 v[168:169], v[148:149], v[172:173] op_sel_hi:[1,0]
	v_pk_mul_f32 v[170:171], v[114:115], v[172:173] op_sel_hi:[1,0]
	v_pk_mul_f32 v[158:159], v[158:159], v[176:177]
	v_pk_mul_f32 v[156:157], v[156:157], v[174:175]
	v_pk_mul_f32 v[162:163], v[162:163], v[180:181]
	v_pk_mul_f32 v[160:161], v[160:161], v[178:179]
	v_pk_mul_f32 v[166:167], v[166:167], v[184:185]
	v_pk_mul_f32 v[164:165], v[164:165], v[182:183]
	v_pk_mul_f32 v[170:171], v[170:171], v[188:189]
	v_pk_mul_f32 v[168:169], v[168:169], v[186:187]
	v_pk_mul_f32 v[172:173], v[156:157], s[36:37] op_sel_hi:[1,0]
	v_pk_mul_f32 v[174:175], v[158:159], s[36:37] op_sel_hi:[1,0]
	v_pk_mul_f32 v[158:159], v[158:159], v[164:165]
	v_pk_mul_f32 v[156:157], v[156:157], v[166:167]
	v_pk_mul_f32 v[164:165], v[160:161], s[36:37] op_sel_hi:[1,0]
	v_pk_mul_f32 v[166:167], v[162:163], s[36:37] op_sel_hi:[1,0]
	v_pk_mul_f32 v[162:163], v[162:163], v[168:169]
	v_pk_mul_f32 v[160:161], v[160:161], v[170:171]
	v_exp_f32_e32 v168, v174
	v_exp_f32_e32 v169, v175
	v_exp_f32_e32 v170, v172
	v_exp_f32_e32 v171, v173
	v_exp_f32_e32 v166, v166
	v_exp_f32_e32 v167, v167
	v_exp_f32_e32 v164, v164
	v_exp_f32_e32 v165, v165
	v_pk_add_f32 v[170:171], v[170:171], 1.0 op_sel_hi:[1,0]
	v_pk_add_f32 v[168:169], v[168:169], 1.0 op_sel_hi:[1,0]
	v_pk_add_f32 v[166:167], v[166:167], 1.0 op_sel_hi:[1,0]
	v_rcp_f32_e32 v168, v168
	v_rcp_f32_e32 v169, v169
	v_rcp_f32_e32 v170, v170
	v_rcp_f32_e32 v171, v171
	v_pk_add_f32 v[164:165], v[164:165], 1.0 op_sel_hi:[1,0]
	v_rcp_f32_e32 v166, v166
	v_rcp_f32_e32 v167, v167
	v_rcp_f32_e32 v164, v164
	v_rcp_f32_e32 v165, v165
	v_pk_mul_f32 v[170:171], v[156:157], v[170:171]
	v_pk_mul_f32 v[156:157], v[158:159], v[168:169]
	v_pk_mul_f32 v[158:159], v[162:163], v[166:167]
	v_cvt_pk_bf16_f32 v156, v156, v157
	v_pk_mul_f32 v[160:161], v[160:161], v[164:165]
	v_cvt_pk_bf16_f32 v157, v170, v171
	v_cvt_pk_bf16_f32 v158, v158, v159
	v_cvt_f32_i32_e32 v62, v62
	v_cvt_pk_bf16_f32 v159, v160, v161
	global_store_dwordx4 v[190:191], v[156:159], off
	v_or_b32_e32 v160, 32, v144
	v_ashrrev_i32_e32 v161, 31, v160
	v_or_b32_e32 v156, 16, v144
	v_ashrrev_i32_e32 v157, 31, v156
	v_lshl_add_u64 v[158:159], v[156:157], 2, s[22:23]
	s_nop 0
	v_mad_i64_i32 v[156:157], s[54:55], v156, s74, v[146:147]
	v_lshl_add_u64 v[156:157], v[156:157], 0, v[116:117]
	v_lshl_add_u64 v[162:163], v[160:161], 2, s[22:23]
	v_cvt_f32_i32_e32 v61, v61
	v_cvt_f32_i32_e32 v60, v60
	v_cvt_f32_i32_e32 v59, v59
	v_cvt_f32_i32_e32 v58, v58
	v_cvt_f32_i32_e32 v57, v57
	v_cvt_f32_i32_e32 v56, v56
	v_cvt_f32_i32_e32 v53, v53
	v_cvt_f32_i32_e32 v52, v52
	v_cvt_f32_i32_e32 v55, v55
	v_cvt_f32_i32_e32 v54, v54
	v_cvt_f32_i32_e32 v49, v49
	v_cvt_f32_i32_e32 v48, v48
	v_cvt_f32_i32_e32 v51, v51
	v_cvt_f32_i32_e32 v50, v50
	v_cvt_f32_i32_e32 v47, v47
	v_cvt_f32_i32_e32 v46, v46
	v_cvt_f32_i32_e32 v45, v45
	v_cvt_f32_i32_e32 v44, v44
	v_cvt_f32_i32_e32 v43, v43
	v_cvt_f32_i32_e32 v42, v42
	v_cvt_f32_i32_e32 v41, v41
	v_cvt_f32_i32_e32 v40, v40
	v_cvt_f32_i32_e32 v37, v37
	v_cvt_f32_i32_e32 v36, v36
	v_cvt_f32_i32_e32 v39, v39
	v_cvt_f32_i32_e32 v38, v38
	v_cvt_f32_i32_e32 v33, v33
	v_cvt_f32_i32_e32 v32, v32
	v_cvt_f32_i32_e32 v35, v35
	v_cvt_f32_i32_e32 v34, v34
	v_cvt_f32_i32_e32 v31, v31
	v_cvt_f32_i32_e32 v30, v30
	v_cvt_f32_i32_e32 v29, v29
	v_cvt_f32_i32_e32 v28, v28
	v_cvt_f32_i32_e32 v27, v27
	v_cvt_f32_i32_e32 v26, v26
	v_cvt_f32_i32_e32 v25, v25
	v_cvt_f32_i32_e32 v24, v24
	v_cvt_f32_i32_e32 v21, v21
	v_cvt_f32_i32_e32 v20, v20
	v_cvt_f32_i32_e32 v23, v23
	v_cvt_f32_i32_e32 v22, v22
	v_cvt_f32_i32_e32 v17, v17
	v_cvt_f32_i32_e32 v16, v16
	v_cvt_f32_i32_e32 v19, v19
	v_cvt_f32_i32_e32 v18, v18
	v_cvt_f32_i32_e32 v15, v15
	v_cvt_f32_i32_e32 v14, v14
	v_cvt_f32_i32_e32 v13, v13
	v_cvt_f32_i32_e32 v12, v12
	v_cvt_f32_i32_e32 v11, v11
	v_cvt_f32_i32_e32 v10, v10
	v_cvt_f32_i32_e32 v9, v9
	v_cvt_f32_i32_e32 v8, v8
	v_cvt_f32_i32_e32 v5, v5
	v_cvt_f32_i32_e32 v4, v4
	v_cvt_f32_i32_e32 v7, v7
	v_cvt_f32_i32_e32 v6, v6
	v_cvt_f32_i32_e32 v1, v1
	v_cvt_f32_i32_e32 v0, v0
	v_cvt_f32_i32_e32 v3, v3
	v_cvt_f32_i32_e32 v2, v2
	s_andn2_b64 vcc, exec, s[6:7]
	s_nop 0
	v_pk_mul_f32 v[164:165], v[118:119], v[224:225] op_sel_hi:[1,0]
	v_pk_mul_f32 v[166:167], v[120:121], v[224:225] op_sel_hi:[1,0]
	v_pk_mul_f32 v[168:169], v[122:123], v[224:225] op_sel_hi:[1,0]
	v_pk_mul_f32 v[170:171], v[124:125], v[224:225] op_sel_hi:[1,0]
	v_pk_mul_f32 v[172:173], v[126:127], v[224:225] op_sel_hi:[1,0]
	v_pk_mul_f32 v[174:175], v[112:113], v[224:225] op_sel_hi:[1,0]
	v_pk_mul_f32 v[176:177], v[148:149], v[224:225] op_sel_hi:[1,0]
	v_pk_mul_f32 v[158:159], v[114:115], v[224:225] op_sel_hi:[1,0]
	v_pk_mul_f32 v[108:109], v[166:167], v[108:109]
	v_pk_mul_f32 v[110:111], v[164:165], v[110:111]
	v_pk_mul_f32 v[104:105], v[170:171], v[104:105]
	v_pk_mul_f32 v[106:107], v[168:169], v[106:107]
	v_pk_mul_f32 v[102:103], v[174:175], v[102:103]
	v_pk_mul_f32 v[100:101], v[172:173], v[100:101]
	v_pk_mul_f32 v[98:99], v[158:159], v[98:99]
	v_pk_mul_f32 v[96:97], v[176:177], v[96:97]
	v_pk_mul_f32 v[158:159], v[110:111], s[36:37] op_sel_hi:[1,0]
	v_pk_mul_f32 v[164:165], v[108:109], s[36:37] op_sel_hi:[1,0]
	v_pk_mul_f32 v[100:101], v[108:109], v[100:101]
	v_pk_mul_f32 v[102:103], v[110:111], v[102:103]
	v_pk_mul_f32 v[108:109], v[106:107], s[36:37] op_sel_hi:[1,0]
	v_pk_mul_f32 v[110:111], v[104:105], s[36:37] op_sel_hi:[1,0]
	v_pk_mul_f32 v[96:97], v[104:105], v[96:97]
	v_exp_f32_e32 v104, v164
	v_exp_f32_e32 v105, v165
	v_exp_f32_e32 v110, v110
	v_exp_f32_e32 v108, v108
	v_exp_f32_e32 v109, v109
	v_exp_f32_e32 v111, v111
	v_pk_mul_f32 v[98:99], v[106:107], v[98:99]
	v_exp_f32_e32 v106, v158
	v_exp_f32_e32 v107, v159
	v_pk_add_f32 v[104:105], v[104:105], 1.0 op_sel_hi:[1,0]
	v_pk_add_f32 v[108:109], v[108:109], 1.0 op_sel_hi:[1,0]
	v_pk_add_f32 v[110:111], v[110:111], 1.0 op_sel_hi:[1,0]
	v_pk_add_f32 v[106:107], v[106:107], 1.0 op_sel_hi:[1,0]
	v_rcp_f32_e32 v104, v104
	v_rcp_f32_e32 v105, v105
	v_rcp_f32_e32 v110, v110
	v_rcp_f32_e32 v108, v108
	v_rcp_f32_e32 v109, v109
	v_rcp_f32_e32 v111, v111
	v_rcp_f32_e32 v106, v106
	v_rcp_f32_e32 v107, v107
	v_pk_mul_f32 v[100:101], v[100:101], v[104:105]
	v_pk_mul_f32 v[104:105], v[98:99], v[108:109]
	v_pk_mul_f32 v[98:99], v[96:97], v[110:111]
	v_pk_mul_f32 v[102:103], v[102:103], v[106:107]
	v_cvt_pk_bf16_f32 v96, v100, v101
	v_mad_i64_i32 v[100:101], s[54:55], v160, s74, v[146:147]
	v_cvt_pk_bf16_f32 v97, v102, v103
	v_cvt_pk_bf16_f32 v98, v98, v99
	v_cvt_pk_bf16_f32 v99, v104, v105
	global_store_dwordx4 v[156:157], v[96:99], off
	s_nop 0
	v_lshl_add_u64 v[100:101], v[100:101], 0, v[116:117]
	v_or_b32_e32 v98, 48, v144
	v_ashrrev_i32_e32 v99, 31, v98
	v_lshl_add_u64 v[102:103], v[98:99], 2, s[22:23]
	s_nop 0
	v_pk_mul_f32 v[104:105], v[118:119], v[226:227] op_sel_hi:[1,0]
	v_pk_mul_f32 v[106:107], v[120:121], v[226:227] op_sel_hi:[1,0]
	v_pk_mul_f32 v[108:109], v[122:123], v[226:227] op_sel_hi:[1,0]
	v_pk_mul_f32 v[110:111], v[124:125], v[226:227] op_sel_hi:[1,0]
	v_pk_mul_f32 v[156:157], v[126:127], v[226:227] op_sel_hi:[1,0]
	v_pk_mul_f32 v[158:159], v[112:113], v[226:227] op_sel_hi:[1,0]
	v_pk_mul_f32 v[160:161], v[148:149], v[226:227] op_sel_hi:[1,0]
	v_pk_mul_f32 v[96:97], v[114:115], v[226:227] op_sel_hi:[1,0]
	v_pk_mul_f32 v[92:93], v[106:107], v[92:93]
	v_pk_mul_f32 v[94:95], v[104:105], v[94:95]
	v_pk_mul_f32 v[88:89], v[110:111], v[88:89]
	v_pk_mul_f32 v[90:91], v[108:109], v[90:91]
	v_pk_mul_f32 v[86:87], v[158:159], v[86:87]
	v_pk_mul_f32 v[84:85], v[156:157], v[84:85]
	v_pk_mul_f32 v[82:83], v[96:97], v[82:83]
	v_pk_mul_f32 v[80:81], v[160:161], v[80:81]
	v_pk_mul_f32 v[96:97], v[94:95], s[36:37] op_sel_hi:[1,0]
	v_pk_mul_f32 v[104:105], v[92:93], s[36:37] op_sel_hi:[1,0]
	v_pk_mul_f32 v[84:85], v[92:93], v[84:85]
	v_pk_mul_f32 v[86:87], v[94:95], v[86:87]
	v_pk_mul_f32 v[92:93], v[90:91], s[36:37] op_sel_hi:[1,0]
	v_pk_mul_f32 v[94:95], v[88:89], s[36:37] op_sel_hi:[1,0]
	v_pk_mul_f32 v[80:81], v[88:89], v[80:81]
	v_exp_f32_e32 v88, v104
	v_exp_f32_e32 v89, v105
	v_exp_f32_e32 v94, v94
	v_exp_f32_e32 v92, v92
	v_exp_f32_e32 v93, v93
	v_exp_f32_e32 v95, v95
	v_pk_mul_f32 v[82:83], v[90:91], v[82:83]
	v_exp_f32_e32 v90, v96
	v_exp_f32_e32 v91, v97
	v_pk_add_f32 v[88:89], v[88:89], 1.0 op_sel_hi:[1,0]
	v_pk_add_f32 v[92:93], v[92:93], 1.0 op_sel_hi:[1,0]
	v_pk_add_f32 v[94:95], v[94:95], 1.0 op_sel_hi:[1,0]
	v_pk_add_f32 v[90:91], v[90:91], 1.0 op_sel_hi:[1,0]
	v_rcp_f32_e32 v88, v88
	v_rcp_f32_e32 v89, v89
	v_rcp_f32_e32 v94, v94
	v_rcp_f32_e32 v92, v92
	v_rcp_f32_e32 v93, v93
	v_rcp_f32_e32 v95, v95
	v_rcp_f32_e32 v90, v90
	v_rcp_f32_e32 v91, v91
	v_pk_mul_f32 v[84:85], v[84:85], v[88:89]
	v_pk_mul_f32 v[88:89], v[82:83], v[92:93]
	v_pk_mul_f32 v[82:83], v[80:81], v[94:95]
	v_pk_mul_f32 v[86:87], v[86:87], v[90:91]
	v_cvt_pk_bf16_f32 v80, v84, v85
	s_nop 0
	v_cvt_pk_bf16_f32 v81, v86, v87
	v_cvt_pk_bf16_f32 v82, v82, v83
	v_cvt_pk_bf16_f32 v83, v88, v89
	global_store_dwordx4 v[100:101], v[80:83], off
	s_nop 0
	s_nop 0
	v_pk_mul_f32 v[84:85], v[118:119], v[228:229] op_sel_hi:[1,0]
	v_pk_mul_f32 v[86:87], v[120:121], v[228:229] op_sel_hi:[1,0]
	v_pk_mul_f32 v[88:89], v[122:123], v[228:229] op_sel_hi:[1,0]
	v_pk_mul_f32 v[90:91], v[124:125], v[228:229] op_sel_hi:[1,0]
	v_pk_mul_f32 v[92:93], v[126:127], v[228:229] op_sel_hi:[1,0]
	v_pk_mul_f32 v[94:95], v[112:113], v[228:229] op_sel_hi:[1,0]
	v_pk_mul_f32 v[96:97], v[148:149], v[228:229] op_sel_hi:[1,0]
	v_pk_mul_f32 v[80:81], v[114:115], v[228:229] op_sel_hi:[1,0]
	v_pk_mul_f32 v[76:77], v[86:87], v[76:77]
	v_pk_mul_f32 v[78:79], v[84:85], v[78:79]
	v_pk_mul_f32 v[72:73], v[90:91], v[72:73]
	v_pk_mul_f32 v[74:75], v[88:89], v[74:75]
	v_pk_mul_f32 v[70:71], v[94:95], v[70:71]
	v_pk_mul_f32 v[68:69], v[92:93], v[68:69]
	v_pk_mul_f32 v[66:67], v[80:81], v[66:67]
	v_pk_mul_f32 v[64:65], v[96:97], v[64:65]
	v_pk_mul_f32 v[80:81], v[78:79], s[36:37] op_sel_hi:[1,0]
	v_pk_mul_f32 v[84:85], v[76:77], s[36:37] op_sel_hi:[1,0]
	v_pk_mul_f32 v[68:69], v[76:77], v[68:69]
	v_pk_mul_f32 v[70:71], v[78:79], v[70:71]
	v_pk_mul_f32 v[76:77], v[74:75], s[36:37] op_sel_hi:[1,0]
	v_pk_mul_f32 v[78:79], v[72:73], s[36:37] op_sel_hi:[1,0]
	v_pk_mul_f32 v[64:65], v[72:73], v[64:65]
	v_exp_f32_e32 v72, v84
	v_exp_f32_e32 v73, v85
	v_exp_f32_e32 v78, v78
	v_exp_f32_e32 v76, v76
	v_exp_f32_e32 v77, v77
	v_exp_f32_e32 v79, v79
	v_pk_mul_f32 v[66:67], v[74:75], v[66:67]
	v_exp_f32_e32 v74, v80
	v_exp_f32_e32 v75, v81
	v_pk_add_f32 v[72:73], v[72:73], 1.0 op_sel_hi:[1,0]
	v_pk_add_f32 v[76:77], v[76:77], 1.0 op_sel_hi:[1,0]
	v_pk_add_f32 v[78:79], v[78:79], 1.0 op_sel_hi:[1,0]
	v_pk_add_f32 v[74:75], v[74:75], 1.0 op_sel_hi:[1,0]
	v_rcp_f32_e32 v72, v72
	v_rcp_f32_e32 v73, v73
	v_rcp_f32_e32 v78, v78
	v_rcp_f32_e32 v76, v76
	v_rcp_f32_e32 v77, v77
	v_rcp_f32_e32 v79, v79
	v_rcp_f32_e32 v74, v74
	v_rcp_f32_e32 v75, v75
	v_mad_i64_i32 v[82:83], s[54:55], v98, s74, v[146:147]
	v_lshl_add_u64 v[82:83], v[82:83], 0, v[116:117]
	v_pk_mul_f32 v[68:69], v[68:69], v[72:73]
	v_pk_mul_f32 v[72:73], v[66:67], v[76:77]
	v_pk_mul_f32 v[66:67], v[64:65], v[78:79]
	v_pk_mul_f32 v[70:71], v[70:71], v[74:75]
	v_cvt_pk_bf16_f32 v64, v68, v69
	s_nop 0
	v_cvt_pk_bf16_f32 v65, v70, v71
	v_cvt_pk_bf16_f32 v66, v66, v67
	v_cvt_pk_bf16_f32 v67, v72, v73
	global_store_dwordx4 v[82:83], v[64:67], off
	s_nop 0
	s_nop 0
	v_add_u32_e32 v65, 0x80, v144
	v_mad_i64_i32 v[66:67], s[54:55], v65, s74, v[146:147]
	v_lshl_add_u64 v[66:67], v[66:67], 0, v[116:117]
	s_nop 0
	v_pk_mul_f32 v[68:69], v[118:119], v[230:231] op_sel_hi:[1,0]
	v_pk_mul_f32 v[70:71], v[120:121], v[230:231] op_sel_hi:[1,0]
	v_pk_mul_f32 v[72:73], v[122:123], v[230:231] op_sel_hi:[1,0]
	v_pk_mul_f32 v[74:75], v[124:125], v[230:231] op_sel_hi:[1,0]
	v_pk_mul_f32 v[76:77], v[126:127], v[230:231] op_sel_hi:[1,0]
	v_pk_mul_f32 v[78:79], v[112:113], v[230:231] op_sel_hi:[1,0]
	v_pk_mul_f32 v[80:81], v[148:149], v[230:231] op_sel_hi:[1,0]
	v_pk_mul_f32 v[64:65], v[114:115], v[230:231] op_sel_hi:[1,0]
	v_pk_mul_f32 v[60:61], v[70:71], v[60:61]
	v_pk_mul_f32 v[62:63], v[68:69], v[62:63]
	v_pk_mul_f32 v[56:57], v[74:75], v[56:57]
	v_pk_mul_f32 v[58:59], v[72:73], v[58:59]
	v_pk_mul_f32 v[54:55], v[78:79], v[54:55]
	v_pk_mul_f32 v[52:53], v[76:77], v[52:53]
	v_pk_mul_f32 v[50:51], v[64:65], v[50:51]
	v_pk_mul_f32 v[48:49], v[80:81], v[48:49]
	v_pk_mul_f32 v[64:65], v[62:63], s[36:37] op_sel_hi:[1,0]
	v_pk_mul_f32 v[68:69], v[60:61], s[36:37] op_sel_hi:[1,0]
	v_pk_mul_f32 v[52:53], v[60:61], v[52:53]
	v_pk_mul_f32 v[54:55], v[62:63], v[54:55]
	v_pk_mul_f32 v[60:61], v[58:59], s[36:37] op_sel_hi:[1,0]
	v_pk_mul_f32 v[62:63], v[56:57], s[36:37] op_sel_hi:[1,0]
	v_pk_mul_f32 v[48:49], v[56:57], v[48:49]
	v_exp_f32_e32 v56, v68
	v_exp_f32_e32 v57, v69
	v_exp_f32_e32 v62, v62
	v_exp_f32_e32 v60, v60
	v_exp_f32_e32 v61, v61
	v_exp_f32_e32 v63, v63
	v_pk_mul_f32 v[50:51], v[58:59], v[50:51]
	v_exp_f32_e32 v58, v64
	v_exp_f32_e32 v59, v65
	v_pk_add_f32 v[56:57], v[56:57], 1.0 op_sel_hi:[1,0]
	v_pk_add_f32 v[60:61], v[60:61], 1.0 op_sel_hi:[1,0]
	v_pk_add_f32 v[62:63], v[62:63], 1.0 op_sel_hi:[1,0]
	v_pk_add_f32 v[58:59], v[58:59], 1.0 op_sel_hi:[1,0]
	v_rcp_f32_e32 v56, v56
	v_rcp_f32_e32 v57, v57
	v_rcp_f32_e32 v62, v62
	v_rcp_f32_e32 v60, v60
	v_rcp_f32_e32 v61, v61
	v_rcp_f32_e32 v63, v63
	v_rcp_f32_e32 v58, v58
	v_rcp_f32_e32 v59, v59
	v_pk_mul_f32 v[52:53], v[52:53], v[56:57]
	v_pk_mul_f32 v[56:57], v[50:51], v[60:61]
	v_pk_mul_f32 v[50:51], v[48:49], v[62:63]
	v_pk_mul_f32 v[54:55], v[54:55], v[58:59]
	v_cvt_pk_bf16_f32 v48, v52, v53
	s_nop 0
	v_cvt_pk_bf16_f32 v49, v54, v55
	v_cvt_pk_bf16_f32 v50, v50, v51
	v_cvt_pk_bf16_f32 v51, v56, v57
	global_store_dwordx4 v[66:67], v[48:51], off
	s_nop 0
	s_nop 0
	v_add_u32_e32 v49, 0x90, v144
	v_mad_i64_i32 v[50:51], s[54:55], v49, s74, v[146:147]
	v_lshl_add_u64 v[50:51], v[50:51], 0, v[116:117]
	s_nop 0
	v_pk_mul_f32 v[52:53], v[118:119], v[232:233] op_sel_hi:[1,0]
	v_pk_mul_f32 v[54:55], v[120:121], v[232:233] op_sel_hi:[1,0]
	v_pk_mul_f32 v[56:57], v[122:123], v[232:233] op_sel_hi:[1,0]
	v_pk_mul_f32 v[58:59], v[124:125], v[232:233] op_sel_hi:[1,0]
	v_pk_mul_f32 v[60:61], v[126:127], v[232:233] op_sel_hi:[1,0]
	v_pk_mul_f32 v[62:63], v[112:113], v[232:233] op_sel_hi:[1,0]
	v_pk_mul_f32 v[64:65], v[148:149], v[232:233] op_sel_hi:[1,0]
	v_pk_mul_f32 v[48:49], v[114:115], v[232:233] op_sel_hi:[1,0]
	v_pk_mul_f32 v[44:45], v[54:55], v[44:45]
	v_pk_mul_f32 v[46:47], v[52:53], v[46:47]
	v_pk_mul_f32 v[40:41], v[58:59], v[40:41]
	v_pk_mul_f32 v[42:43], v[56:57], v[42:43]
	v_pk_mul_f32 v[38:39], v[62:63], v[38:39]
	v_pk_mul_f32 v[36:37], v[60:61], v[36:37]
	v_pk_mul_f32 v[34:35], v[48:49], v[34:35]
	v_pk_mul_f32 v[32:33], v[64:65], v[32:33]
	v_pk_mul_f32 v[48:49], v[46:47], s[36:37] op_sel_hi:[1,0]
	v_pk_mul_f32 v[52:53], v[44:45], s[36:37] op_sel_hi:[1,0]
	v_pk_mul_f32 v[36:37], v[44:45], v[36:37]
	v_pk_mul_f32 v[38:39], v[46:47], v[38:39]
	v_pk_mul_f32 v[44:45], v[42:43], s[36:37] op_sel_hi:[1,0]
	v_pk_mul_f32 v[46:47], v[40:41], s[36:37] op_sel_hi:[1,0]
	v_pk_mul_f32 v[32:33], v[40:41], v[32:33]
	v_exp_f32_e32 v40, v52
	v_exp_f32_e32 v41, v53
	v_exp_f32_e32 v46, v46
	v_exp_f32_e32 v44, v44
	v_exp_f32_e32 v45, v45
	v_exp_f32_e32 v47, v47
	v_pk_mul_f32 v[34:35], v[42:43], v[34:35]
	v_exp_f32_e32 v42, v48
	v_exp_f32_e32 v43, v49
	v_pk_add_f32 v[40:41], v[40:41], 1.0 op_sel_hi:[1,0]
	v_pk_add_f32 v[44:45], v[44:45], 1.0 op_sel_hi:[1,0]
	v_pk_add_f32 v[46:47], v[46:47], 1.0 op_sel_hi:[1,0]
	v_pk_add_f32 v[42:43], v[42:43], 1.0 op_sel_hi:[1,0]
	v_rcp_f32_e32 v40, v40
	v_rcp_f32_e32 v41, v41
	v_rcp_f32_e32 v46, v46
	v_rcp_f32_e32 v44, v44
	v_rcp_f32_e32 v45, v45
	v_rcp_f32_e32 v47, v47
	v_rcp_f32_e32 v42, v42
	v_rcp_f32_e32 v43, v43
	v_pk_mul_f32 v[36:37], v[36:37], v[40:41]
	v_pk_mul_f32 v[40:41], v[34:35], v[44:45]
	v_pk_mul_f32 v[34:35], v[32:33], v[46:47]
	v_pk_mul_f32 v[38:39], v[38:39], v[42:43]
	v_cvt_pk_bf16_f32 v32, v36, v37
	s_nop 0
	v_cvt_pk_bf16_f32 v33, v38, v39
	v_cvt_pk_bf16_f32 v34, v34, v35
	v_cvt_pk_bf16_f32 v35, v40, v41
	global_store_dwordx4 v[50:51], v[32:35], off
	s_nop 0
	s_nop 0
	v_add_u32_e32 v33, 0xa0, v144
	v_mad_i64_i32 v[34:35], s[54:55], v33, s74, v[146:147]
	v_lshl_add_u64 v[34:35], v[34:35], 0, v[116:117]
	s_nop 0
	v_pk_mul_f32 v[36:37], v[118:119], v[234:235] op_sel_hi:[1,0]
	v_pk_mul_f32 v[38:39], v[120:121], v[234:235] op_sel_hi:[1,0]
	v_pk_mul_f32 v[40:41], v[122:123], v[234:235] op_sel_hi:[1,0]
	v_pk_mul_f32 v[42:43], v[124:125], v[234:235] op_sel_hi:[1,0]
	v_pk_mul_f32 v[44:45], v[126:127], v[234:235] op_sel_hi:[1,0]
	v_pk_mul_f32 v[46:47], v[112:113], v[234:235] op_sel_hi:[1,0]
	v_pk_mul_f32 v[48:49], v[148:149], v[234:235] op_sel_hi:[1,0]
	v_pk_mul_f32 v[32:33], v[114:115], v[234:235] op_sel_hi:[1,0]
	v_pk_mul_f32 v[28:29], v[38:39], v[28:29]
	v_pk_mul_f32 v[30:31], v[36:37], v[30:31]
	v_pk_mul_f32 v[24:25], v[42:43], v[24:25]
	v_pk_mul_f32 v[26:27], v[40:41], v[26:27]
	v_pk_mul_f32 v[22:23], v[46:47], v[22:23]
	v_pk_mul_f32 v[20:21], v[44:45], v[20:21]
	v_pk_mul_f32 v[18:19], v[32:33], v[18:19]
	v_pk_mul_f32 v[16:17], v[48:49], v[16:17]
	v_pk_mul_f32 v[32:33], v[30:31], s[36:37] op_sel_hi:[1,0]
	v_pk_mul_f32 v[36:37], v[28:29], s[36:37] op_sel_hi:[1,0]
	v_pk_mul_f32 v[20:21], v[28:29], v[20:21]
	v_pk_mul_f32 v[22:23], v[30:31], v[22:23]
	v_pk_mul_f32 v[28:29], v[26:27], s[36:37] op_sel_hi:[1,0]
	v_pk_mul_f32 v[30:31], v[24:25], s[36:37] op_sel_hi:[1,0]
	v_pk_mul_f32 v[16:17], v[24:25], v[16:17]
	v_exp_f32_e32 v24, v36
	v_exp_f32_e32 v25, v37
	v_exp_f32_e32 v30, v30
	v_exp_f32_e32 v28, v28
	v_exp_f32_e32 v29, v29
	v_exp_f32_e32 v31, v31
	v_pk_mul_f32 v[18:19], v[26:27], v[18:19]
	v_exp_f32_e32 v26, v32
	v_exp_f32_e32 v27, v33
	v_pk_add_f32 v[24:25], v[24:25], 1.0 op_sel_hi:[1,0]
	v_pk_add_f32 v[28:29], v[28:29], 1.0 op_sel_hi:[1,0]
	v_pk_add_f32 v[30:31], v[30:31], 1.0 op_sel_hi:[1,0]
	v_pk_add_f32 v[26:27], v[26:27], 1.0 op_sel_hi:[1,0]
	v_rcp_f32_e32 v24, v24
	v_rcp_f32_e32 v25, v25
	v_rcp_f32_e32 v30, v30
	v_rcp_f32_e32 v28, v28
	v_rcp_f32_e32 v29, v29
	v_rcp_f32_e32 v31, v31
	v_rcp_f32_e32 v26, v26
	v_rcp_f32_e32 v27, v27
	v_pk_mul_f32 v[20:21], v[20:21], v[24:25]
	v_pk_mul_f32 v[24:25], v[18:19], v[28:29]
	v_pk_mul_f32 v[18:19], v[16:17], v[30:31]
	v_pk_mul_f32 v[22:23], v[22:23], v[26:27]
	v_cvt_pk_bf16_f32 v16, v20, v21
	s_nop 0
	v_cvt_pk_bf16_f32 v17, v22, v23
	v_cvt_pk_bf16_f32 v18, v18, v19
	v_cvt_pk_bf16_f32 v19, v24, v25
	global_store_dwordx4 v[34:35], v[16:19], off
	s_nop 0
	s_nop 0
	v_add_u32_e32 v17, 0xb0, v144
	v_mad_i64_i32 v[18:19], s[6:7], v17, s74, v[146:147]
	v_lshl_add_u64 v[18:19], v[18:19], 0, v[116:117]
	s_mov_b64 s[6:7], -1
	s_nop 0
	v_pk_mul_f32 v[20:21], v[118:119], v[236:237] op_sel_hi:[1,0]
	v_pk_mul_f32 v[22:23], v[120:121], v[236:237] op_sel_hi:[1,0]
	v_pk_mul_f32 v[24:25], v[122:123], v[236:237] op_sel_hi:[1,0]
	v_pk_mul_f32 v[26:27], v[124:125], v[236:237] op_sel_hi:[1,0]
	v_pk_mul_f32 v[28:29], v[126:127], v[236:237] op_sel_hi:[1,0]
	v_pk_mul_f32 v[30:31], v[112:113], v[236:237] op_sel_hi:[1,0]
	v_pk_mul_f32 v[32:33], v[148:149], v[236:237] op_sel_hi:[1,0]
	v_pk_mul_f32 v[16:17], v[114:115], v[236:237] op_sel_hi:[1,0]
	v_pk_mul_f32 v[12:13], v[22:23], v[12:13]
	v_pk_mul_f32 v[14:15], v[20:21], v[14:15]
	v_pk_mul_f32 v[8:9], v[26:27], v[8:9]
	v_pk_mul_f32 v[10:11], v[24:25], v[10:11]
	v_pk_mul_f32 v[6:7], v[30:31], v[6:7]
	v_pk_mul_f32 v[4:5], v[28:29], v[4:5]
	v_pk_mul_f32 v[2:3], v[16:17], v[2:3]
	v_pk_mul_f32 v[0:1], v[32:33], v[0:1]
	v_pk_mul_f32 v[16:17], v[14:15], s[36:37] op_sel_hi:[1,0]
	v_pk_mul_f32 v[20:21], v[12:13], s[36:37] op_sel_hi:[1,0]
	v_pk_mul_f32 v[4:5], v[12:13], v[4:5]
	v_pk_mul_f32 v[6:7], v[14:15], v[6:7]
	v_pk_mul_f32 v[12:13], v[10:11], s[36:37] op_sel_hi:[1,0]
	v_pk_mul_f32 v[14:15], v[8:9], s[36:37] op_sel_hi:[1,0]
	v_pk_mul_f32 v[0:1], v[8:9], v[0:1]
	v_exp_f32_e32 v8, v20
	v_exp_f32_e32 v9, v21
	v_exp_f32_e32 v14, v14
	v_exp_f32_e32 v12, v12
	v_exp_f32_e32 v13, v13
	v_exp_f32_e32 v15, v15
	v_pk_mul_f32 v[2:3], v[10:11], v[2:3]
	v_exp_f32_e32 v10, v16
	v_exp_f32_e32 v11, v17
	v_pk_add_f32 v[8:9], v[8:9], 1.0 op_sel_hi:[1,0]
	v_pk_add_f32 v[12:13], v[12:13], 1.0 op_sel_hi:[1,0]
	v_pk_add_f32 v[14:15], v[14:15], 1.0 op_sel_hi:[1,0]
	v_pk_add_f32 v[10:11], v[10:11], 1.0 op_sel_hi:[1,0]
	v_rcp_f32_e32 v8, v8
	v_rcp_f32_e32 v9, v9
	v_rcp_f32_e32 v14, v14
	v_rcp_f32_e32 v12, v12
	v_rcp_f32_e32 v13, v13
	v_rcp_f32_e32 v15, v15
	v_rcp_f32_e32 v10, v10
	v_rcp_f32_e32 v11, v11
	v_pk_mul_f32 v[4:5], v[4:5], v[8:9]
	v_pk_mul_f32 v[8:9], v[2:3], v[12:13]
	v_pk_mul_f32 v[2:3], v[0:1], v[14:15]
	v_pk_mul_f32 v[6:7], v[6:7], v[10:11]
	v_cvt_pk_bf16_f32 v0, v4, v5
	s_nop 0
	v_cvt_pk_bf16_f32 v1, v6, v7
	v_cvt_pk_bf16_f32 v2, v2, v3
	v_cvt_pk_bf16_f32 v3, v8, v9
	global_store_dwordx4 v[18:19], v[0:3], off
	s_cbranch_vccnz .LBB0_767
	s_andn2_b64 vcc, exec, s[12:13]
	s_cbranch_vccnz .LBB0_766
	s_barrier
	s_branch .LBB0_766

.LBB0_981:
	s_mov_b32 s40, 0
	v_cvt_f32_i32_e32 v175, v125
	v_mbcnt_lo_u32_b32 v144, -1, s40
	v_mbcnt_hi_u32_b32 v148, -1, v144
	s_lshl_b32 s40, s74, 8
	v_ashrrev_i32_e32 v144, 1, v148
	s_or_b32 s40, s40, s57
	v_and_b32_e32 v144, -8, v144
	v_add_u32_e32 v146, s40, v144
	s_lshl_b32 s40, s73, 8
	s_add_i32 s40, s40, s56
	v_ashrrev_i32_e32 v147, 31, v146
	v_and_or_b32 v148, v148, 15, s40
	v_lshl_add_u64 v[144:145], v[146:147], 2, s[18:19]
	v_ashrrev_i32_e32 v149, 31, v148
	global_load_dwordx4 v[156:159], v[144:145], off offset:16
	global_load_dwordx4 v[160:163], v[144:145], off
	global_load_dwordx4 v[164:167], v[144:145], off offset:528
	global_load_dwordx4 v[168:171], v[144:145], off offset:512
	v_lshl_add_u64 v[144:145], v[148:149], 2, s[16:17]
	global_load_dword v224, v[144:145], off offset:64
	global_load_dword v226, v[144:145], off offset:128
	global_load_dword v228, v[144:145], off offset:192
	global_load_dword v230, v[144:145], off offset:512
	global_load_dword v232, v[144:145], off offset:576
	global_load_dword v234, v[144:145], off offset:640
	global_load_dword v236, v[144:145], off offset:704
	global_load_dword v172, v[144:145], off
	v_cvt_f32_i32_e32 v174, v124
	v_cvt_f32_i32_e32 v177, v127
	v_cvt_f32_i32_e32 v176, v126
	v_cvt_f32_i32_e32 v187, v113
	v_cvt_f32_i32_e32 v186, v112
	v_lshlrev_b64 v[112:113], 13, v[148:149]
	v_cvt_f32_i32_e32 v179, v121
	v_cvt_f32_i32_e32 v178, v120
	v_cvt_f32_i32_e32 v181, v123
	v_cvt_f32_i32_e32 v180, v122
	v_lshl_add_u64 v[112:113], s[12:13], 0, v[112:113]
	v_lshlrev_b64 v[150:151], 1, v[146:147]
	v_cvt_f32_i32_e32 v183, v117
	v_cvt_f32_i32_e32 v182, v116
	v_cvt_f32_i32_e32 v185, v119
	v_cvt_f32_i32_e32 v184, v118
	v_cvt_f32_i32_e32 v189, v115
	v_cvt_f32_i32_e32 v188, v114
	v_lshl_add_u64 v[120:121], v[112:113], 0, v[150:151]
	v_or_b32_e32 v190, 16, v148
	v_ashrrev_i32_e32 v191, 31, v190
	v_lshl_add_u64 v[192:193], v[190:191], 2, s[16:17]
	v_cvt_f32_i32_e32 v109, v109
	v_cvt_f32_i32_e32 v108, v108
	v_cvt_f32_i32_e32 v111, v111
	v_cvt_f32_i32_e32 v110, v110
	v_cvt_f32_i32_e32 v105, v105
	v_cvt_f32_i32_e32 v104, v104
	v_cvt_f32_i32_e32 v107, v107
	v_cvt_f32_i32_e32 v106, v106
	v_cvt_f32_i32_e32 v97, v97
	v_cvt_f32_i32_e32 v96, v96
	v_cvt_f32_i32_e32 v99, v99
	v_cvt_f32_i32_e32 v98, v98
	v_cvt_f32_i32_e32 v101, v101
	v_cvt_f32_i32_e32 v100, v100
	v_cvt_f32_i32_e32 v103, v103
	v_cvt_f32_i32_e32 v102, v102
	v_cvt_f32_i32_e32 v93, v93
	v_cvt_f32_i32_e32 v92, v92
	v_cvt_f32_i32_e32 v95, v95
	v_cvt_f32_i32_e32 v94, v94
	v_cvt_f32_i32_e32 v89, v89
	v_cvt_f32_i32_e32 v88, v88
	v_cvt_f32_i32_e32 v91, v91
	v_cvt_f32_i32_e32 v90, v90
	v_cvt_f32_i32_e32 v81, v81
	v_cvt_f32_i32_e32 v80, v80
	v_cvt_f32_i32_e32 v83, v83
	v_cvt_f32_i32_e32 v82, v82
	v_cvt_f32_i32_e32 v85, v85
	v_cvt_f32_i32_e32 v84, v84
	v_cvt_f32_i32_e32 v87, v87
	v_cvt_f32_i32_e32 v86, v86
	v_cvt_f32_i32_e32 v77, v77
	v_cvt_f32_i32_e32 v76, v76
	v_cvt_f32_i32_e32 v79, v79
	v_cvt_f32_i32_e32 v78, v78
	v_cvt_f32_i32_e32 v73, v73
	v_cvt_f32_i32_e32 v72, v72
	v_cvt_f32_i32_e32 v75, v75
	v_cvt_f32_i32_e32 v74, v74
	v_cvt_f32_i32_e32 v65, v65
	v_cvt_f32_i32_e32 v64, v64
	v_cvt_f32_i32_e32 v67, v67
	v_cvt_f32_i32_e32 v66, v66
	v_cvt_f32_i32_e32 v69, v69
	v_cvt_f32_i32_e32 v68, v68
	v_cvt_f32_i32_e32 v71, v71
	v_cvt_f32_i32_e32 v70, v70
	v_cvt_f32_i32_e32 v61, v61
	v_cvt_f32_i32_e32 v60, v60
	v_cvt_f32_i32_e32 v63, v63
	v_cvt_f32_i32_e32 v62, v62
	v_cvt_f32_i32_e32 v57, v57
	s_waitcnt vmcnt(0)
	v_pk_mul_f32 v[114:115], v[158:159], s[24:25] op_sel_hi:[1,0]
	v_pk_mul_f32 v[112:113], v[162:163], s[24:25] op_sel_hi:[1,0]
	v_pk_mul_f32 v[122:123], v[160:161], s[24:25] op_sel_hi:[1,0]
	v_pk_mul_f32 v[124:125], v[156:157], s[24:25] op_sel_hi:[1,0]
	v_pk_mul_f32 v[156:157], v[122:123], v[172:173] op_sel_hi:[1,0]
	v_pk_mul_f32 v[158:159], v[112:113], v[172:173] op_sel_hi:[1,0]
	v_pk_mul_f32 v[116:117], v[170:171], s[24:25] op_sel_hi:[1,0]
	v_pk_mul_f32 v[126:127], v[168:169], s[24:25] op_sel_hi:[1,0]
	v_pk_mul_f32 v[118:119], v[166:167], s[24:25] op_sel_hi:[1,0]
	v_pk_mul_f32 v[146:147], v[164:165], s[24:25] op_sel_hi:[1,0]
	v_pk_mul_f32 v[160:161], v[124:125], v[172:173] op_sel_hi:[1,0]
	v_pk_mul_f32 v[162:163], v[114:115], v[172:173] op_sel_hi:[1,0]
	v_pk_mul_f32 v[158:159], v[158:159], v[176:177]
	v_pk_mul_f32 v[156:157], v[156:157], v[174:175]
	v_pk_mul_f32 v[164:165], v[126:127], v[172:173] op_sel_hi:[1,0]
	v_pk_mul_f32 v[166:167], v[116:117], v[172:173] op_sel_hi:[1,0]
	v_pk_mul_f32 v[168:169], v[146:147], v[172:173] op_sel_hi:[1,0]
	v_pk_mul_f32 v[170:171], v[118:119], v[172:173] op_sel_hi:[1,0]
	v_pk_mul_f32 v[162:163], v[162:163], v[180:181]
	v_pk_mul_f32 v[160:161], v[160:161], v[178:179]
	v_cvt_pk_bf16_f32 v156, v156, v157
	v_cvt_pk_bf16_f32 v157, v158, v159
	v_pk_mul_f32 v[166:167], v[166:167], v[184:185]
	v_cvt_pk_bf16_f32 v158, v160, v161
	v_cvt_pk_bf16_f32 v159, v162, v163
	v_pk_mul_f32 v[164:165], v[164:165], v[182:183]
	v_pk_mul_f32 v[170:171], v[170:171], v[188:189]
	v_pk_mul_f32 v[168:169], v[168:169], v[186:187]
	global_store_dwordx4 v[120:121], v[156:159], off
	v_lshlrev_b64 v[160:161], 13, v[190:191]
	v_lshl_add_u64 v[160:161], s[12:13], 0, v[160:161]
	v_cvt_pk_bf16_f32 v156, v164, v165
	v_cvt_pk_bf16_f32 v157, v166, v167
	v_cvt_pk_bf16_f32 v158, v168, v169
	v_cvt_pk_bf16_f32 v159, v170, v171
	global_store_dwordx4 v[120:121], v[156:159], off offset:256
	s_nop 0
	v_lshl_add_u64 v[160:161], v[160:161], 0, v[150:151]
	v_or_b32_e32 v158, 32, v148
	v_ashrrev_i32_e32 v159, 31, v158
	v_lshl_add_u64 v[162:163], v[158:159], 2, s[16:17]
	v_cvt_f32_i32_e32 v56, v56
	v_cvt_f32_i32_e32 v59, v59
	v_cvt_f32_i32_e32 v58, v58
	v_cvt_f32_i32_e32 v49, v49
	v_cvt_f32_i32_e32 v48, v48
	v_cvt_f32_i32_e32 v51, v51
	v_cvt_f32_i32_e32 v50, v50
	v_cvt_f32_i32_e32 v53, v53
	v_cvt_f32_i32_e32 v52, v52
	v_cvt_f32_i32_e32 v55, v55
	v_cvt_f32_i32_e32 v54, v54
	v_cvt_f32_i32_e32 v45, v45
	v_cvt_f32_i32_e32 v44, v44
	v_cvt_f32_i32_e32 v47, v47
	v_cvt_f32_i32_e32 v46, v46
	v_cvt_f32_i32_e32 v41, v41
	v_cvt_f32_i32_e32 v40, v40
	v_cvt_f32_i32_e32 v43, v43
	v_cvt_f32_i32_e32 v42, v42
	v_cvt_f32_i32_e32 v33, v33
	v_cvt_f32_i32_e32 v32, v32
	v_cvt_f32_i32_e32 v35, v35
	v_cvt_f32_i32_e32 v34, v34
	v_cvt_f32_i32_e32 v37, v37
	v_cvt_f32_i32_e32 v36, v36
	v_cvt_f32_i32_e32 v39, v39
	v_cvt_f32_i32_e32 v38, v38
	v_cvt_f32_i32_e32 v29, v29
	v_cvt_f32_i32_e32 v28, v28
	v_cvt_f32_i32_e32 v31, v31
	v_cvt_f32_i32_e32 v30, v30
	v_cvt_f32_i32_e32 v25, v25
	v_cvt_f32_i32_e32 v24, v24
	v_cvt_f32_i32_e32 v27, v27
	v_cvt_f32_i32_e32 v26, v26
	v_cvt_f32_i32_e32 v17, v17
	v_cvt_f32_i32_e32 v16, v16
	v_cvt_f32_i32_e32 v19, v19
	v_cvt_f32_i32_e32 v18, v18
	v_cvt_f32_i32_e32 v21, v21
	v_cvt_f32_i32_e32 v20, v20
	v_cvt_f32_i32_e32 v23, v23
	v_cvt_f32_i32_e32 v22, v22
	v_cvt_f32_i32_e32 v13, v13
	v_cvt_f32_i32_e32 v12, v12
	v_cvt_f32_i32_e32 v15, v15
	v_cvt_f32_i32_e32 v14, v14
	v_cvt_f32_i32_e32 v9, v9
	v_cvt_f32_i32_e32 v8, v8
	v_cvt_f32_i32_e32 v11, v11
	v_cvt_f32_i32_e32 v10, v10
	v_cvt_f32_i32_e32 v1, v1
	v_cvt_f32_i32_e32 v0, v0
	v_cvt_f32_i32_e32 v3, v3
	v_cvt_f32_i32_e32 v2, v2
	v_cvt_f32_i32_e32 v5, v5
	v_cvt_f32_i32_e32 v4, v4
	v_cvt_f32_i32_e32 v7, v7
	v_cvt_f32_i32_e32 v6, v6
	s_nop 0
	v_pk_mul_f32 v[164:165], v[122:123], v[224:225] op_sel_hi:[1,0]
	v_pk_mul_f32 v[166:167], v[112:113], v[224:225] op_sel_hi:[1,0]
	v_pk_mul_f32 v[168:169], v[124:125], v[224:225] op_sel_hi:[1,0]
	v_pk_mul_f32 v[170:171], v[114:115], v[224:225] op_sel_hi:[1,0]
	v_pk_mul_f32 v[172:173], v[126:127], v[224:225] op_sel_hi:[1,0]
	v_pk_mul_f32 v[174:175], v[116:117], v[224:225] op_sel_hi:[1,0]
	v_pk_mul_f32 v[176:177], v[146:147], v[224:225] op_sel_hi:[1,0]
	v_pk_mul_f32 v[156:157], v[118:119], v[224:225] op_sel_hi:[1,0]
	v_pk_mul_f32 v[110:111], v[166:167], v[110:111]
	v_pk_mul_f32 v[108:109], v[164:165], v[108:109]
	v_pk_mul_f32 v[106:107], v[170:171], v[106:107]
	v_pk_mul_f32 v[104:105], v[168:169], v[104:105]
	v_pk_mul_f32 v[156:157], v[156:157], v[98:99]
	v_pk_mul_f32 v[164:165], v[176:177], v[96:97]
	v_cvt_pk_bf16_f32 v96, v108, v109
	v_cvt_pk_bf16_f32 v97, v110, v111
	v_cvt_pk_bf16_f32 v98, v104, v105
	v_cvt_pk_bf16_f32 v99, v106, v107
	v_pk_mul_f32 v[102:103], v[174:175], v[102:103]
	v_pk_mul_f32 v[100:101], v[172:173], v[100:101]
	global_store_dwordx4 v[160:161], v[96:99], off
	s_nop 1
	v_cvt_pk_bf16_f32 v96, v100, v101
	v_cvt_pk_bf16_f32 v97, v102, v103
	v_cvt_pk_bf16_f32 v98, v164, v165
	v_cvt_pk_bf16_f32 v99, v156, v157
	global_store_dwordx4 v[160:161], v[96:99], off offset:256
	s_nop 0
	v_lshlrev_b64 v[100:101], 13, v[158:159]
	v_or_b32_e32 v98, 48, v148
	v_lshl_add_u64 v[100:101], s[12:13], 0, v[100:101]
	v_ashrrev_i32_e32 v99, 31, v98
	v_lshl_add_u64 v[100:101], v[100:101], 0, v[150:151]
	v_lshl_add_u64 v[102:103], v[98:99], 2, s[16:17]
	s_nop 0
	v_pk_mul_f32 v[104:105], v[122:123], v[226:227] op_sel_hi:[1,0]
	v_pk_mul_f32 v[106:107], v[112:113], v[226:227] op_sel_hi:[1,0]
	v_pk_mul_f32 v[108:109], v[124:125], v[226:227] op_sel_hi:[1,0]
	v_pk_mul_f32 v[110:111], v[114:115], v[226:227] op_sel_hi:[1,0]
	v_pk_mul_f32 v[148:149], v[126:127], v[226:227] op_sel_hi:[1,0]
	v_pk_mul_f32 v[156:157], v[116:117], v[226:227] op_sel_hi:[1,0]
	v_pk_mul_f32 v[158:159], v[146:147], v[226:227] op_sel_hi:[1,0]
	v_pk_mul_f32 v[96:97], v[118:119], v[226:227] op_sel_hi:[1,0]
	v_pk_mul_f32 v[94:95], v[106:107], v[94:95]
	v_pk_mul_f32 v[92:93], v[104:105], v[92:93]
	v_pk_mul_f32 v[90:91], v[110:111], v[90:91]
	v_pk_mul_f32 v[88:89], v[108:109], v[88:89]
	v_pk_mul_f32 v[96:97], v[96:97], v[82:83]
	v_pk_mul_f32 v[104:105], v[158:159], v[80:81]
	v_cvt_pk_bf16_f32 v80, v92, v93
	v_cvt_pk_bf16_f32 v81, v94, v95
	v_cvt_pk_bf16_f32 v82, v88, v89
	v_cvt_pk_bf16_f32 v83, v90, v91
	v_pk_mul_f32 v[86:87], v[156:157], v[86:87]
	v_pk_mul_f32 v[84:85], v[148:149], v[84:85]
	global_store_dwordx4 v[100:101], v[80:83], off
	s_nop 1
	v_cvt_pk_bf16_f32 v80, v84, v85
	v_cvt_pk_bf16_f32 v81, v86, v87
	v_cvt_pk_bf16_f32 v82, v104, v105
	v_cvt_pk_bf16_f32 v83, v96, v97
	global_store_dwordx4 v[100:101], v[80:83], off offset:256
	s_nop 0
	s_nop 0
	v_pk_mul_f32 v[84:85], v[122:123], v[228:229] op_sel_hi:[1,0]
	v_lshlrev_b64 v[82:83], 13, v[98:99]
	v_lshl_add_u64 v[82:83], s[12:13], 0, v[82:83]
	v_pk_mul_f32 v[86:87], v[112:113], v[228:229] op_sel_hi:[1,0]
	v_pk_mul_f32 v[88:89], v[124:125], v[228:229] op_sel_hi:[1,0]
	v_pk_mul_f32 v[90:91], v[114:115], v[228:229] op_sel_hi:[1,0]
	v_pk_mul_f32 v[92:93], v[126:127], v[228:229] op_sel_hi:[1,0]
	v_pk_mul_f32 v[94:95], v[116:117], v[228:229] op_sel_hi:[1,0]
	v_pk_mul_f32 v[96:97], v[146:147], v[228:229] op_sel_hi:[1,0]
	v_pk_mul_f32 v[80:81], v[118:119], v[228:229] op_sel_hi:[1,0]
	v_lshl_add_u64 v[82:83], v[82:83], 0, v[150:151]
	v_pk_mul_f32 v[78:79], v[86:87], v[78:79]
	v_pk_mul_f32 v[76:77], v[84:85], v[76:77]
	v_pk_mul_f32 v[74:75], v[90:91], v[74:75]
	v_pk_mul_f32 v[72:73], v[88:89], v[72:73]
	v_pk_mul_f32 v[80:81], v[80:81], v[66:67]
	v_pk_mul_f32 v[84:85], v[96:97], v[64:65]
	v_cvt_pk_bf16_f32 v64, v76, v77
	v_cvt_pk_bf16_f32 v65, v78, v79
	v_cvt_pk_bf16_f32 v66, v72, v73
	v_cvt_pk_bf16_f32 v67, v74, v75
	v_pk_mul_f32 v[70:71], v[94:95], v[70:71]
	v_pk_mul_f32 v[68:69], v[92:93], v[68:69]
	global_store_dwordx4 v[82:83], v[64:67], off
	s_nop 1
	v_cvt_pk_bf16_f32 v64, v68, v69
	v_cvt_pk_bf16_f32 v65, v70, v71
	v_cvt_pk_bf16_f32 v66, v84, v85
	v_cvt_pk_bf16_f32 v67, v80, v81
	global_store_dwordx4 v[82:83], v[64:67], off offset:256
	s_nop 0
	v_add_co_u32_e32 v68, vcc, s63, v120
	v_lshl_add_u64 v[66:67], v[120:121], 0, s[26:27]
	s_nop 0
	v_addc_co_u32_e32 v69, vcc, 0, v121, vcc
	s_nop 0
	v_pk_mul_f32 v[70:71], v[122:123], v[230:231] op_sel_hi:[1,0]
	v_pk_mul_f32 v[72:73], v[112:113], v[230:231] op_sel_hi:[1,0]
	v_pk_mul_f32 v[74:75], v[124:125], v[230:231] op_sel_hi:[1,0]
	v_pk_mul_f32 v[76:77], v[114:115], v[230:231] op_sel_hi:[1,0]
	v_pk_mul_f32 v[78:79], v[126:127], v[230:231] op_sel_hi:[1,0]
	v_pk_mul_f32 v[80:81], v[116:117], v[230:231] op_sel_hi:[1,0]
	v_pk_mul_f32 v[82:83], v[146:147], v[230:231] op_sel_hi:[1,0]
	v_pk_mul_f32 v[64:65], v[118:119], v[230:231] op_sel_hi:[1,0]
	v_pk_mul_f32 v[62:63], v[72:73], v[62:63]
	v_pk_mul_f32 v[60:61], v[70:71], v[60:61]
	v_pk_mul_f32 v[58:59], v[76:77], v[58:59]
	v_pk_mul_f32 v[56:57], v[74:75], v[56:57]
	v_pk_mul_f32 v[64:65], v[64:65], v[50:51]
	v_pk_mul_f32 v[70:71], v[82:83], v[48:49]
	v_cvt_pk_bf16_f32 v48, v60, v61
	v_cvt_pk_bf16_f32 v49, v62, v63
	v_cvt_pk_bf16_f32 v50, v56, v57
	v_cvt_pk_bf16_f32 v51, v58, v59
	v_pk_mul_f32 v[54:55], v[80:81], v[54:55]
	v_pk_mul_f32 v[52:53], v[78:79], v[52:53]
	global_store_dwordx4 v[68:69], v[48:51], off
	s_nop 1
	v_cvt_pk_bf16_f32 v48, v52, v53
	v_cvt_pk_bf16_f32 v49, v54, v55
	v_cvt_pk_bf16_f32 v50, v70, v71
	v_cvt_pk_bf16_f32 v51, v64, v65
	global_store_dwordx4 v[66:67], v[48:51], off offset:256
	s_nop 0
	v_add_co_u32_e32 v52, vcc, s65, v120
	v_lshl_add_u64 v[50:51], v[120:121], 0, s[28:29]
	s_nop 0
	v_addc_co_u32_e32 v53, vcc, 0, v121, vcc
	s_nop 0
	v_pk_mul_f32 v[54:55], v[122:123], v[232:233] op_sel_hi:[1,0]
	v_pk_mul_f32 v[56:57], v[112:113], v[232:233] op_sel_hi:[1,0]
	v_pk_mul_f32 v[58:59], v[124:125], v[232:233] op_sel_hi:[1,0]
	v_pk_mul_f32 v[60:61], v[114:115], v[232:233] op_sel_hi:[1,0]
	v_pk_mul_f32 v[62:63], v[126:127], v[232:233] op_sel_hi:[1,0]
	v_pk_mul_f32 v[64:65], v[116:117], v[232:233] op_sel_hi:[1,0]
	v_pk_mul_f32 v[66:67], v[146:147], v[232:233] op_sel_hi:[1,0]
	v_pk_mul_f32 v[48:49], v[118:119], v[232:233] op_sel_hi:[1,0]
	v_pk_mul_f32 v[46:47], v[56:57], v[46:47]
	v_pk_mul_f32 v[44:45], v[54:55], v[44:45]
	v_pk_mul_f32 v[42:43], v[60:61], v[42:43]
	v_pk_mul_f32 v[40:41], v[58:59], v[40:41]
	v_pk_mul_f32 v[48:49], v[48:49], v[34:35]
	v_pk_mul_f32 v[54:55], v[66:67], v[32:33]
	v_cvt_pk_bf16_f32 v32, v44, v45
	v_cvt_pk_bf16_f32 v33, v46, v47
	v_cvt_pk_bf16_f32 v34, v40, v41
	v_cvt_pk_bf16_f32 v35, v42, v43
	v_pk_mul_f32 v[38:39], v[64:65], v[38:39]
	v_pk_mul_f32 v[36:37], v[62:63], v[36:37]
	global_store_dwordx4 v[52:53], v[32:35], off
	s_nop 1
	v_cvt_pk_bf16_f32 v32, v36, v37
	v_cvt_pk_bf16_f32 v33, v38, v39
	v_cvt_pk_bf16_f32 v34, v54, v55
	v_cvt_pk_bf16_f32 v35, v48, v49
	global_store_dwordx4 v[50:51], v[32:35], off offset:256
	s_nop 0
	v_add_co_u32_e32 v36, vcc, s67, v120
	v_lshl_add_u64 v[34:35], v[120:121], 0, s[30:31]
	s_nop 0
	v_addc_co_u32_e32 v37, vcc, 0, v121, vcc
	s_and_b64 vcc, exec, s[6:7]
	s_nop 0
	v_pk_mul_f32 v[38:39], v[122:123], v[234:235] op_sel_hi:[1,0]
	v_pk_mul_f32 v[40:41], v[112:113], v[234:235] op_sel_hi:[1,0]
	v_pk_mul_f32 v[42:43], v[124:125], v[234:235] op_sel_hi:[1,0]
	v_pk_mul_f32 v[44:45], v[114:115], v[234:235] op_sel_hi:[1,0]
	v_pk_mul_f32 v[46:47], v[126:127], v[234:235] op_sel_hi:[1,0]
	v_pk_mul_f32 v[48:49], v[116:117], v[234:235] op_sel_hi:[1,0]
	v_pk_mul_f32 v[50:51], v[146:147], v[234:235] op_sel_hi:[1,0]
	v_pk_mul_f32 v[32:33], v[118:119], v[234:235] op_sel_hi:[1,0]
	v_pk_mul_f32 v[30:31], v[40:41], v[30:31]
	v_pk_mul_f32 v[28:29], v[38:39], v[28:29]
	v_pk_mul_f32 v[26:27], v[44:45], v[26:27]
	v_pk_mul_f32 v[24:25], v[42:43], v[24:25]
	v_pk_mul_f32 v[32:33], v[32:33], v[18:19]
	v_pk_mul_f32 v[38:39], v[50:51], v[16:17]
	v_cvt_pk_bf16_f32 v16, v28, v29
	v_cvt_pk_bf16_f32 v17, v30, v31
	v_cvt_pk_bf16_f32 v18, v24, v25
	v_cvt_pk_bf16_f32 v19, v26, v27
	v_pk_mul_f32 v[22:23], v[48:49], v[22:23]
	v_pk_mul_f32 v[20:21], v[46:47], v[20:21]
	global_store_dwordx4 v[36:37], v[16:19], off
	s_nop 1
	v_cvt_pk_bf16_f32 v16, v20, v21
	v_cvt_pk_bf16_f32 v17, v22, v23
	v_cvt_pk_bf16_f32 v18, v38, v39
	v_cvt_pk_bf16_f32 v19, v32, v33
	global_store_dwordx4 v[34:35], v[16:19], off offset:256
	s_nop 0
	v_add_co_u32_e64 v20, s[6:7], s70, v120
	v_lshl_add_u64 v[18:19], v[120:121], 0, s[36:37]
	s_nop 0
	v_addc_co_u32_e64 v21, s[6:7], 0, v121, s[6:7]
	s_mov_b64 s[6:7], -1
	s_nop 0
	v_pk_mul_f32 v[22:23], v[122:123], v[236:237] op_sel_hi:[1,0]
	v_pk_mul_f32 v[24:25], v[112:113], v[236:237] op_sel_hi:[1,0]
	v_pk_mul_f32 v[26:27], v[124:125], v[236:237] op_sel_hi:[1,0]
	v_pk_mul_f32 v[28:29], v[114:115], v[236:237] op_sel_hi:[1,0]
	v_pk_mul_f32 v[30:31], v[126:127], v[236:237] op_sel_hi:[1,0]
	v_pk_mul_f32 v[32:33], v[116:117], v[236:237] op_sel_hi:[1,0]
	v_pk_mul_f32 v[34:35], v[146:147], v[236:237] op_sel_hi:[1,0]
	v_pk_mul_f32 v[16:17], v[118:119], v[236:237] op_sel_hi:[1,0]
	v_pk_mul_f32 v[14:15], v[24:25], v[14:15]
	v_pk_mul_f32 v[12:13], v[22:23], v[12:13]
	v_pk_mul_f32 v[10:11], v[28:29], v[10:11]
	v_pk_mul_f32 v[8:9], v[26:27], v[8:9]
	v_pk_mul_f32 v[16:17], v[16:17], v[2:3]
	v_pk_mul_f32 v[22:23], v[34:35], v[0:1]
	v_cvt_pk_bf16_f32 v0, v12, v13
	v_cvt_pk_bf16_f32 v1, v14, v15
	v_cvt_pk_bf16_f32 v2, v8, v9
	v_cvt_pk_bf16_f32 v3, v10, v11
	v_pk_mul_f32 v[6:7], v[32:33], v[6:7]
	v_pk_mul_f32 v[4:5], v[30:31], v[4:5]
	global_store_dwordx4 v[20:21], v[0:3], off
	s_nop 1
	v_cvt_pk_bf16_f32 v0, v4, v5
	v_cvt_pk_bf16_f32 v1, v6, v7
	v_cvt_pk_bf16_f32 v2, v22, v23
	v_cvt_pk_bf16_f32 v3, v16, v17
	global_store_dwordx4 v[18:19], v[0:3], off offset:256
	s_cbranch_vccnz .LBB0_970
	s_andn2_b64 vcc, exec, s[10:11]
	s_cbranch_vccnz .LBB0_969
	s_barrier
	s_branch .LBB0_969
